# P1 gelu epilogues: the three constant multiplies of the tanh-form gelu folded into one fma (5 plain + 2 transcendental VALU per element instead of 8 + 2)
# baseline (speedup 1.0000x reference)
.Lp1_e_norm:
	v_and_b32_e32 v194, 15, v222
	v_bfe_u32 v195, v222, 4, 2
	v_bfe_u32 v196, v222, 6, 2
	v_lshrrev_b32_e32 v197, 8, v222
	v_lshl_or_b32 v198, v197, 7, v194
	v_lshlrev_b32_e32 v199, 2, v195
	v_lshl_or_b32 v199, v196, 6, v199
	s_lshr_b32 s2, s4, 3
	s_and_b32 s3, s4, 7
	s_lshl_b32 s3, s3, 9
	s_add_i32 s7, s4, 0xffffff80
	s_lshl_b32 s2, s2, 18
	s_add_i32 s2, s2, s3
	s_add_i32 s2, s2, 0xaaae500
	s_lshl_b32 s7, s7, 15
	s_add_i32 s7, s7, 0xbaae500
	s_cmp_lt_u32 s4, 0x80
	s_cselect_b32 s2, s2, s7
	s_movk_i32 s7, 0x200
	s_cselect_b32 s7, 0x1000, s7
	v_readlane_b32 s22, v254, 14
	v_readlane_b32 s23, v254, 15
	s_nop 3
	s_add_u32 s22, s22, s2
	s_addc_u32 s23, s23, 0
	v_and_b32_e32 v190, 63, v222
	v_lshrrev_b32_e32 v191, 3, v190
	v_and_b32_e32 v192, 7, v190
	v_lshl_or_b32 v193, v196, 10, v191
	v_mul_lo_u32 v193, v193, s7
	v_lshlrev_b32_e32 v189, 4, v192
	v_lshl_add_u32 v189, v197, 8, v189
	v_add_u32_e32 v193, v193, v189
	v_lshrrev_b32_e32 v188, 6, v222
	v_mul_u32_u24_e32 v188, 0x2400, v188
	v_add_u32_e32 v188, 0x10000, v188
	v_mul_u32_u24_e32 v189, 0x90, v191
	v_lshl_add_u32 v189, v192, 4, v189
	v_add_u32_e32 v189, v189, v188
	v_mul_u32_u24_e32 v187, 0x240, v195
	v_lshl_add_u32 v187, v194, 1, v187
	v_add_u32_e32 v187, v187, v188
	v_xor_b32_e32 v186, 16, v190
	v_lshlrev_b32_e32 v186, 2, v186
	v_xor_b32_e32 v185, 32, v190
	v_lshlrev_b32_e32 v185, 2, v185
	s_add_i32 s2, s53, s95
	s_cmp_lt_i32 s2, s9
	s_cselect_b32 s21, 1, 0
	s_cselect_b32 s53, s2, s53
	s_lshr_b32 s2, s53, 5
	s_mul_hi_u32 s2, s2, 0xcccccccd
	s_lshr_b32 s2, s2, 2
	s_lshl_b32 s3, s2, 4
	s_mul_i32 s2, s2, 0xa0
	s_sub_i32 s2, s53, s2
	s_lshr_b32 s2, s2, 4
	s_and_b32 s6, s53, 15
	s_add_i32 s3, s3, s6
	s_sub_i32 s28, s53, s58
	s_lshr_b32 s28, s28, 4
	s_add_i32 s28, s28, 8
	s_or_b32 s6, s6, 0x80
	s_cmp_ge_i32 s53, s58
	s_cselect_b32 s6, s6, s3
	s_cselect_b32 s28, s28, s2
	s_lshl_b32 s2, s6, 19
	s_add_u32 s12, s64, s2
	s_addc_u32 s13, s65, 0
	s_lshl_b32 s2, s28, 19
	s_add_u32 s14, s34, s2
	s_addc_u32 s15, s35, 0
	s_mov_b32 m0, s18
	s_nop 0
	global_load_lds_dwordx4 v1, s[12:13]
	s_add_i32 m0, s18, 0x2000
	s_add_u32 s16, s12, 0x20000
	s_addc_u32 s17, s13, 0
	global_load_lds_dwordx4 v1, s[16:17]
	s_add_i32 m0, s18, 0x4000
	s_add_u32 s16, s12, 0x40000
	s_addc_u32 s17, s13, 0
	global_load_lds_dwordx4 v1, s[16:17]
	s_add_i32 m0, s18, 0x6000
	s_add_u32 s16, s12, 0x60000
	s_addc_u32 s17, s13, 0
	global_load_lds_dwordx4 v1, s[16:17]
	s_add_i32 m0, s18, 0x8000
	s_nop 0
	global_load_lds_dwordx4 v1, s[14:15]
	s_add_i32 m0, s18, 0xa000
	s_add_u32 s16, s14, 0x20000
	s_addc_u32 s17, s15, 0
	global_load_lds_dwordx4 v1, s[16:17]
	s_add_i32 m0, s18, 0xc000
	s_add_u32 s16, s14, 0x40000
	s_addc_u32 s17, s15, 0
	global_load_lds_dwordx4 v1, s[16:17]
	s_add_i32 m0, s18, 0xe000
	s_add_u32 s16, s14, 0x60000
	s_addc_u32 s17, s15, 0
	global_load_lds_dwordx4 v1, s[16:17]
	s_lshl_b32 s3, s7, 3
	v_mov_b32_e32 v182, 0xbdd2d3e8
	v_mov_b32_e32 v183, 0xc0135761
	v_mul_f32_e32 v130, v126, v126
	v_mul_f32_e32 v131, v127, v127
	v_mul_f32_e32 v132, v128, v128
	v_mul_f32_e32 v133, v129, v129
	v_fma_f32 v130, v130, v182, v183
	v_fma_f32 v131, v131, v182, v183
	v_fma_f32 v132, v132, v182, v183
	v_fma_f32 v133, v133, v182, v183
	v_mul_f32_e32 v130, v126, v130
	v_mul_f32_e32 v131, v127, v131
	v_mul_f32_e32 v132, v128, v132
	v_mul_f32_e32 v133, v129, v133
	v_exp_f32_e32 v130, v130
	v_exp_f32_e32 v131, v131
	v_exp_f32_e32 v132, v132
	v_exp_f32_e32 v133, v133
	v_add_f32_e32 v130, 1.0, v130
	v_add_f32_e32 v131, 1.0, v131
	v_add_f32_e32 v132, 1.0, v132
	v_add_f32_e32 v133, 1.0, v133
	v_rcp_f32_e32 v130, v130
	v_rcp_f32_e32 v131, v131
	v_rcp_f32_e32 v132, v132
	v_rcp_f32_e32 v133, v133
	s_nop 0
	v_mul_f32_e32 v126, v126, v130
	v_mul_f32_e32 v127, v127, v131
	v_mul_f32_e32 v128, v128, v132
	v_mul_f32_e32 v129, v129, v133
	v_mul_f32_e32 v134, v122, v122
	v_mul_f32_e32 v135, v123, v123
	v_mul_f32_e32 v136, v124, v124
	v_mul_f32_e32 v137, v125, v125
	v_fma_f32 v134, v134, v182, v183
	v_fma_f32 v135, v135, v182, v183
	v_fma_f32 v136, v136, v182, v183
	v_fma_f32 v137, v137, v182, v183
	v_mul_f32_e32 v134, v122, v134
	v_mul_f32_e32 v135, v123, v135
	v_mul_f32_e32 v136, v124, v136
	v_mul_f32_e32 v137, v125, v137
	v_exp_f32_e32 v134, v134
	v_exp_f32_e32 v135, v135
	v_exp_f32_e32 v136, v136
	v_exp_f32_e32 v137, v137
	v_add_f32_e32 v134, 1.0, v134
	v_add_f32_e32 v135, 1.0, v135
	v_add_f32_e32 v136, 1.0, v136
	v_add_f32_e32 v137, 1.0, v137
	v_rcp_f32_e32 v134, v134
	v_rcp_f32_e32 v135, v135
	v_rcp_f32_e32 v136, v136
	v_rcp_f32_e32 v137, v137
	s_nop 0
	v_mul_f32_e32 v122, v122, v134
	v_mul_f32_e32 v123, v123, v135
	v_mul_f32_e32 v124, v124, v136
	v_mul_f32_e32 v125, v125, v137
	v_mul_f32_e32 v130, v118, v118
	v_mul_f32_e32 v131, v119, v119
	v_mul_f32_e32 v132, v120, v120
	v_mul_f32_e32 v133, v121, v121
	v_fma_f32 v130, v130, v182, v183
	v_fma_f32 v131, v131, v182, v183
	v_fma_f32 v132, v132, v182, v183
	v_fma_f32 v133, v133, v182, v183
	v_mul_f32_e32 v130, v118, v130
	v_mul_f32_e32 v131, v119, v131
	v_mul_f32_e32 v132, v120, v132
	v_mul_f32_e32 v133, v121, v133
	v_exp_f32_e32 v130, v130
	v_exp_f32_e32 v131, v131
	v_exp_f32_e32 v132, v132
	v_exp_f32_e32 v133, v133
	v_add_f32_e32 v130, 1.0, v130
	v_add_f32_e32 v131, 1.0, v131
	v_add_f32_e32 v132, 1.0, v132
	v_add_f32_e32 v133, 1.0, v133
	v_rcp_f32_e32 v130, v130
	v_rcp_f32_e32 v131, v131
	v_rcp_f32_e32 v132, v132
	v_rcp_f32_e32 v133, v133
	s_nop 0
	v_mul_f32_e32 v118, v118, v130
	v_mul_f32_e32 v119, v119, v131
	v_mul_f32_e32 v120, v120, v132
	v_mul_f32_e32 v121, v121, v133
	v_mul_f32_e32 v134, v114, v114
	v_mul_f32_e32 v135, v115, v115
	v_mul_f32_e32 v136, v116, v116
	v_mul_f32_e32 v137, v117, v117
	v_fma_f32 v134, v134, v182, v183
	v_fma_f32 v135, v135, v182, v183
	v_fma_f32 v136, v136, v182, v183
	v_fma_f32 v137, v137, v182, v183
	v_mul_f32_e32 v134, v114, v134
	v_mul_f32_e32 v135, v115, v135
	v_mul_f32_e32 v136, v116, v136
	v_mul_f32_e32 v137, v117, v137
	v_exp_f32_e32 v134, v134
	v_exp_f32_e32 v135, v135
	v_exp_f32_e32 v136, v136
	v_exp_f32_e32 v137, v137
	v_add_f32_e32 v134, 1.0, v134
	v_add_f32_e32 v135, 1.0, v135
	v_add_f32_e32 v136, 1.0, v136
	v_add_f32_e32 v137, 1.0, v137
	v_rcp_f32_e32 v134, v134
	v_rcp_f32_e32 v135, v135
	v_rcp_f32_e32 v136, v136
	v_rcp_f32_e32 v137, v137
	s_nop 0
	v_mul_f32_e32 v114, v114, v134
	v_mul_f32_e32 v115, v115, v135
	v_mul_f32_e32 v116, v116, v136
	v_mul_f32_e32 v117, v117, v137
	v_pk_mul_f32 v[136:137], v[126:127], v[126:127]
	v_pk_mul_f32 v[138:139], v[128:129], v[128:129]
	v_add_f32_e32 v140, 0, v136
	v_add_f32_e32 v140, v137, v140
	v_add_f32_e32 v140, v138, v140
	v_add_f32_e32 v140, v139, v140
	v_pk_mul_f32 v[136:137], v[122:123], v[122:123]
	v_pk_mul_f32 v[138:139], v[124:125], v[124:125]
	v_add_f32_e32 v140, v136, v140
	v_add_f32_e32 v140, v137, v140
	v_add_f32_e32 v140, v138, v140
	v_add_f32_e32 v140, v139, v140
	v_pk_mul_f32 v[136:137], v[118:119], v[118:119]
	v_pk_mul_f32 v[138:139], v[120:121], v[120:121]
	v_add_f32_e32 v140, v136, v140
	v_add_f32_e32 v140, v137, v140
	v_add_f32_e32 v140, v138, v140
	v_add_f32_e32 v140, v139, v140
	v_pk_mul_f32 v[136:137], v[114:115], v[114:115]
	v_pk_mul_f32 v[138:139], v[116:117], v[116:117]
	v_add_f32_e32 v140, v136, v140
	v_add_f32_e32 v140, v137, v140
	v_add_f32_e32 v140, v138, v140
	v_add_f32_e32 v140, v139, v140
	ds_bpermute_b32 v141, v186, v140
	s_waitcnt lgkmcnt(0)
	v_add_f32_e32 v140, v140, v141
	ds_bpermute_b32 v141, v185, v140
	s_waitcnt lgkmcnt(0)
	v_add_f32_e32 v140, v140, v141
	v_mov_b32_e32 v141, 0x358637bd
	v_fmamk_f32 v140, v140, 0x3c800000, v141
	v_mul_f32_e32 v141, 0x4b800000, v140
	v_cmp_gt_f32_e32 vcc, 0x800000, v140
	s_nop 1
	v_cndmask_b32_e32 v140, v140, v141, vcc
	v_rsq_f32_e32 v140, v140
	s_nop 0
	v_mul_f32_e32 v141, 0x45800000, v140
	v_cndmask_b32_e32 v144, v140, v141, vcc
	v_mul_f32_e32 v130, v110, v110
	v_mul_f32_e32 v131, v111, v111
	v_mul_f32_e32 v132, v112, v112
	v_mul_f32_e32 v133, v113, v113
	v_fma_f32 v130, v130, v182, v183
	v_fma_f32 v131, v131, v182, v183
	v_fma_f32 v132, v132, v182, v183
	v_fma_f32 v133, v133, v182, v183
	v_mul_f32_e32 v130, v110, v130
	v_mul_f32_e32 v131, v111, v131
	v_mul_f32_e32 v132, v112, v132
	v_mul_f32_e32 v133, v113, v133
	v_exp_f32_e32 v130, v130
	v_exp_f32_e32 v131, v131
	v_exp_f32_e32 v132, v132
	v_exp_f32_e32 v133, v133
	v_add_f32_e32 v130, 1.0, v130
	v_add_f32_e32 v131, 1.0, v131
	v_add_f32_e32 v132, 1.0, v132
	v_add_f32_e32 v133, 1.0, v133
	v_rcp_f32_e32 v130, v130
	v_rcp_f32_e32 v131, v131
	v_rcp_f32_e32 v132, v132
	v_rcp_f32_e32 v133, v133
	s_nop 0
	v_mul_f32_e32 v110, v110, v130
	v_mul_f32_e32 v111, v111, v131
	v_mul_f32_e32 v112, v112, v132
	v_mul_f32_e32 v113, v113, v133
	v_mul_f32_e32 v134, v106, v106
	v_mul_f32_e32 v135, v107, v107
	v_mul_f32_e32 v136, v108, v108
	v_mul_f32_e32 v137, v109, v109
	v_fma_f32 v134, v134, v182, v183
	v_fma_f32 v135, v135, v182, v183
	v_fma_f32 v136, v136, v182, v183
	v_fma_f32 v137, v137, v182, v183
	v_mul_f32_e32 v134, v106, v134
	v_mul_f32_e32 v135, v107, v135
	v_mul_f32_e32 v136, v108, v136
	v_mul_f32_e32 v137, v109, v137
	v_exp_f32_e32 v134, v134
	v_exp_f32_e32 v135, v135
	v_exp_f32_e32 v136, v136
	v_exp_f32_e32 v137, v137
	v_add_f32_e32 v134, 1.0, v134
	v_add_f32_e32 v135, 1.0, v135
	v_add_f32_e32 v136, 1.0, v136
	v_add_f32_e32 v137, 1.0, v137
	v_rcp_f32_e32 v134, v134
	v_rcp_f32_e32 v135, v135
	v_rcp_f32_e32 v136, v136
	v_rcp_f32_e32 v137, v137
	s_nop 0
	v_mul_f32_e32 v106, v106, v134
	v_mul_f32_e32 v107, v107, v135
	v_mul_f32_e32 v108, v108, v136
	v_mul_f32_e32 v109, v109, v137
	v_mul_f32_e32 v130, v102, v102
	v_mul_f32_e32 v131, v103, v103
	v_mul_f32_e32 v132, v104, v104
	v_mul_f32_e32 v133, v105, v105
	v_fma_f32 v130, v130, v182, v183
	v_fma_f32 v131, v131, v182, v183
	v_fma_f32 v132, v132, v182, v183
	v_fma_f32 v133, v133, v182, v183
	v_mul_f32_e32 v130, v102, v130
	v_mul_f32_e32 v131, v103, v131
	v_mul_f32_e32 v132, v104, v132
	v_mul_f32_e32 v133, v105, v133
	v_exp_f32_e32 v130, v130
	v_exp_f32_e32 v131, v131
	v_exp_f32_e32 v132, v132
	v_exp_f32_e32 v133, v133
	v_add_f32_e32 v130, 1.0, v130
	v_add_f32_e32 v131, 1.0, v131
	v_add_f32_e32 v132, 1.0, v132
	v_add_f32_e32 v133, 1.0, v133
	v_rcp_f32_e32 v130, v130
	v_rcp_f32_e32 v131, v131
	v_rcp_f32_e32 v132, v132
	v_rcp_f32_e32 v133, v133
	s_nop 0
	v_mul_f32_e32 v102, v102, v130
	v_mul_f32_e32 v103, v103, v131
	v_mul_f32_e32 v104, v104, v132
	v_mul_f32_e32 v105, v105, v133
	v_mul_f32_e32 v134, v98, v98
	v_mul_f32_e32 v135, v99, v99
	v_mul_f32_e32 v136, v100, v100
	v_mul_f32_e32 v137, v101, v101
	v_fma_f32 v134, v134, v182, v183
	v_fma_f32 v135, v135, v182, v183
	v_fma_f32 v136, v136, v182, v183
	v_fma_f32 v137, v137, v182, v183
	v_mul_f32_e32 v134, v98, v134
	v_mul_f32_e32 v135, v99, v135
	v_mul_f32_e32 v136, v100, v136
	v_mul_f32_e32 v137, v101, v137
	v_exp_f32_e32 v134, v134
	v_exp_f32_e32 v135, v135
	v_exp_f32_e32 v136, v136
	v_exp_f32_e32 v137, v137
	v_add_f32_e32 v134, 1.0, v134
	v_add_f32_e32 v135, 1.0, v135
	v_add_f32_e32 v136, 1.0, v136
	v_add_f32_e32 v137, 1.0, v137
	v_rcp_f32_e32 v134, v134
	v_rcp_f32_e32 v135, v135
	v_rcp_f32_e32 v136, v136
	v_rcp_f32_e32 v137, v137
	s_nop 0
	v_mul_f32_e32 v98, v98, v134
	v_mul_f32_e32 v99, v99, v135
	v_mul_f32_e32 v100, v100, v136
	v_mul_f32_e32 v101, v101, v137
	v_pk_mul_f32 v[136:137], v[110:111], v[110:111]
	v_pk_mul_f32 v[138:139], v[112:113], v[112:113]
	v_add_f32_e32 v140, 0, v136
	v_add_f32_e32 v140, v137, v140
	v_add_f32_e32 v140, v138, v140
	v_add_f32_e32 v140, v139, v140
	v_pk_mul_f32 v[136:137], v[106:107], v[106:107]
	v_pk_mul_f32 v[138:139], v[108:109], v[108:109]
	v_add_f32_e32 v140, v136, v140
	v_add_f32_e32 v140, v137, v140
	v_add_f32_e32 v140, v138, v140
	v_add_f32_e32 v140, v139, v140
	v_pk_mul_f32 v[136:137], v[102:103], v[102:103]
	v_pk_mul_f32 v[138:139], v[104:105], v[104:105]
	v_add_f32_e32 v140, v136, v140
	v_add_f32_e32 v140, v137, v140
	v_add_f32_e32 v140, v138, v140
	v_add_f32_e32 v140, v139, v140
	v_pk_mul_f32 v[136:137], v[98:99], v[98:99]
	v_pk_mul_f32 v[138:139], v[100:101], v[100:101]
	v_add_f32_e32 v140, v136, v140
	v_add_f32_e32 v140, v137, v140
	v_add_f32_e32 v140, v138, v140
	v_add_f32_e32 v140, v139, v140
	ds_bpermute_b32 v141, v186, v140
	s_waitcnt lgkmcnt(0)
	v_add_f32_e32 v140, v140, v141
	ds_bpermute_b32 v141, v185, v140
	s_waitcnt lgkmcnt(0)
	v_add_f32_e32 v140, v140, v141
	v_mov_b32_e32 v141, 0x358637bd
	v_fmamk_f32 v140, v140, 0x3c800000, v141
	v_mul_f32_e32 v141, 0x4b800000, v140
	v_cmp_gt_f32_e32 vcc, 0x800000, v140
	s_nop 1
	v_cndmask_b32_e32 v140, v140, v141, vcc
	v_rsq_f32_e32 v140, v140
	s_nop 0
	v_mul_f32_e32 v141, 0x45800000, v140
	v_cndmask_b32_e32 v145, v140, v141, vcc
	v_mul_f32_e32 v130, v94, v94
	v_mul_f32_e32 v131, v95, v95
	v_mul_f32_e32 v132, v96, v96
	v_mul_f32_e32 v133, v97, v97
	v_fma_f32 v130, v130, v182, v183
	v_fma_f32 v131, v131, v182, v183
	v_fma_f32 v132, v132, v182, v183
	v_fma_f32 v133, v133, v182, v183
	v_mul_f32_e32 v130, v94, v130
	v_mul_f32_e32 v131, v95, v131
	v_mul_f32_e32 v132, v96, v132
	v_mul_f32_e32 v133, v97, v133
	v_exp_f32_e32 v130, v130
	v_exp_f32_e32 v131, v131
	v_exp_f32_e32 v132, v132
	v_exp_f32_e32 v133, v133
	v_add_f32_e32 v130, 1.0, v130
	v_add_f32_e32 v131, 1.0, v131
	v_add_f32_e32 v132, 1.0, v132
	v_add_f32_e32 v133, 1.0, v133
	v_rcp_f32_e32 v130, v130
	v_rcp_f32_e32 v131, v131
	v_rcp_f32_e32 v132, v132
	v_rcp_f32_e32 v133, v133
	s_nop 0
	v_mul_f32_e32 v94, v94, v130
	v_mul_f32_e32 v95, v95, v131
	v_mul_f32_e32 v96, v96, v132
	v_mul_f32_e32 v97, v97, v133
	v_mul_f32_e32 v134, v90, v90
	v_mul_f32_e32 v135, v91, v91
	v_mul_f32_e32 v136, v92, v92
	v_mul_f32_e32 v137, v93, v93
	v_fma_f32 v134, v134, v182, v183
	v_fma_f32 v135, v135, v182, v183
	v_fma_f32 v136, v136, v182, v183
	v_fma_f32 v137, v137, v182, v183
	v_mul_f32_e32 v134, v90, v134
	v_mul_f32_e32 v135, v91, v135
	v_mul_f32_e32 v136, v92, v136
	v_mul_f32_e32 v137, v93, v137
	v_exp_f32_e32 v134, v134
	v_exp_f32_e32 v135, v135
	v_exp_f32_e32 v136, v136
	v_exp_f32_e32 v137, v137
	v_add_f32_e32 v134, 1.0, v134
	v_add_f32_e32 v135, 1.0, v135
	v_add_f32_e32 v136, 1.0, v136
	v_add_f32_e32 v137, 1.0, v137
	v_rcp_f32_e32 v134, v134
	v_rcp_f32_e32 v135, v135
	v_rcp_f32_e32 v136, v136
	v_rcp_f32_e32 v137, v137
	s_nop 0
	v_mul_f32_e32 v90, v90, v134
	v_mul_f32_e32 v91, v91, v135
	v_mul_f32_e32 v92, v92, v136
	v_mul_f32_e32 v93, v93, v137
	v_mul_f32_e32 v130, v86, v86
	v_mul_f32_e32 v131, v87, v87
	v_mul_f32_e32 v132, v88, v88
	v_mul_f32_e32 v133, v89, v89
	v_fma_f32 v130, v130, v182, v183
	v_fma_f32 v131, v131, v182, v183
	v_fma_f32 v132, v132, v182, v183
	v_fma_f32 v133, v133, v182, v183
	v_mul_f32_e32 v130, v86, v130
	v_mul_f32_e32 v131, v87, v131
	v_mul_f32_e32 v132, v88, v132
	v_mul_f32_e32 v133, v89, v133
	v_exp_f32_e32 v130, v130
	v_exp_f32_e32 v131, v131
	v_exp_f32_e32 v132, v132
	v_exp_f32_e32 v133, v133
	v_add_f32_e32 v130, 1.0, v130
	v_add_f32_e32 v131, 1.0, v131
	v_add_f32_e32 v132, 1.0, v132
	v_add_f32_e32 v133, 1.0, v133
	v_rcp_f32_e32 v130, v130
	v_rcp_f32_e32 v131, v131
	v_rcp_f32_e32 v132, v132
	v_rcp_f32_e32 v133, v133
	s_nop 0
	v_mul_f32_e32 v86, v86, v130
	v_mul_f32_e32 v87, v87, v131
	v_mul_f32_e32 v88, v88, v132
	v_mul_f32_e32 v89, v89, v133
	v_mul_f32_e32 v134, v82, v82
	v_mul_f32_e32 v135, v83, v83
	v_mul_f32_e32 v136, v84, v84
	v_mul_f32_e32 v137, v85, v85
	v_fma_f32 v134, v134, v182, v183
	v_fma_f32 v135, v135, v182, v183
	v_fma_f32 v136, v136, v182, v183
	v_fma_f32 v137, v137, v182, v183
	v_mul_f32_e32 v134, v82, v134
	v_mul_f32_e32 v135, v83, v135
	v_mul_f32_e32 v136, v84, v136
	v_mul_f32_e32 v137, v85, v137
	v_exp_f32_e32 v134, v134
	v_exp_f32_e32 v135, v135
	v_exp_f32_e32 v136, v136
	v_exp_f32_e32 v137, v137
	v_add_f32_e32 v134, 1.0, v134
	v_add_f32_e32 v135, 1.0, v135
	v_add_f32_e32 v136, 1.0, v136
	v_add_f32_e32 v137, 1.0, v137
	v_rcp_f32_e32 v134, v134
	v_rcp_f32_e32 v135, v135
	v_rcp_f32_e32 v136, v136
	v_rcp_f32_e32 v137, v137
	s_nop 0
	v_mul_f32_e32 v82, v82, v134
	v_mul_f32_e32 v83, v83, v135
	v_mul_f32_e32 v84, v84, v136
	v_mul_f32_e32 v85, v85, v137
	v_pk_mul_f32 v[136:137], v[94:95], v[94:95]
	v_pk_mul_f32 v[138:139], v[96:97], v[96:97]
	v_add_f32_e32 v140, 0, v136
	v_add_f32_e32 v140, v137, v140
	v_add_f32_e32 v140, v138, v140
	v_add_f32_e32 v140, v139, v140
	v_pk_mul_f32 v[136:137], v[90:91], v[90:91]
	v_pk_mul_f32 v[138:139], v[92:93], v[92:93]
	v_add_f32_e32 v140, v136, v140
	v_add_f32_e32 v140, v137, v140
	v_add_f32_e32 v140, v138, v140
	v_add_f32_e32 v140, v139, v140
	v_pk_mul_f32 v[136:137], v[86:87], v[86:87]
	v_pk_mul_f32 v[138:139], v[88:89], v[88:89]
	v_add_f32_e32 v140, v136, v140
	v_add_f32_e32 v140, v137, v140
	v_add_f32_e32 v140, v138, v140
	v_add_f32_e32 v140, v139, v140
	v_pk_mul_f32 v[136:137], v[82:83], v[82:83]
	v_pk_mul_f32 v[138:139], v[84:85], v[84:85]
	v_add_f32_e32 v140, v136, v140
	v_add_f32_e32 v140, v137, v140
	v_add_f32_e32 v140, v138, v140
	v_add_f32_e32 v140, v139, v140
	ds_bpermute_b32 v141, v186, v140
	s_waitcnt lgkmcnt(0)
	v_add_f32_e32 v140, v140, v141
	ds_bpermute_b32 v141, v185, v140
	s_waitcnt lgkmcnt(0)
	v_add_f32_e32 v140, v140, v141
	v_mov_b32_e32 v141, 0x358637bd
	v_fmamk_f32 v140, v140, 0x3c800000, v141
	v_mul_f32_e32 v141, 0x4b800000, v140
	v_cmp_gt_f32_e32 vcc, 0x800000, v140
	s_nop 1
	v_cndmask_b32_e32 v140, v140, v141, vcc
	v_rsq_f32_e32 v140, v140
	s_nop 0
	v_mul_f32_e32 v141, 0x45800000, v140
	v_cndmask_b32_e32 v146, v140, v141, vcc
	v_mul_f32_e32 v130, v78, v78
	v_mul_f32_e32 v131, v79, v79
	v_mul_f32_e32 v132, v80, v80
	v_mul_f32_e32 v133, v81, v81
	v_fma_f32 v130, v130, v182, v183
	v_fma_f32 v131, v131, v182, v183
	v_fma_f32 v132, v132, v182, v183
	v_fma_f32 v133, v133, v182, v183
	v_mul_f32_e32 v130, v78, v130
	v_mul_f32_e32 v131, v79, v131
	v_mul_f32_e32 v132, v80, v132
	v_mul_f32_e32 v133, v81, v133
	v_exp_f32_e32 v130, v130
	v_exp_f32_e32 v131, v131
	v_exp_f32_e32 v132, v132
	v_exp_f32_e32 v133, v133
	v_add_f32_e32 v130, 1.0, v130
	v_add_f32_e32 v131, 1.0, v131
	v_add_f32_e32 v132, 1.0, v132
	v_add_f32_e32 v133, 1.0, v133
	v_rcp_f32_e32 v130, v130
	v_rcp_f32_e32 v131, v131
	v_rcp_f32_e32 v132, v132
	v_rcp_f32_e32 v133, v133
	s_nop 0
	v_mul_f32_e32 v78, v78, v130
	v_mul_f32_e32 v79, v79, v131
	v_mul_f32_e32 v80, v80, v132
	v_mul_f32_e32 v81, v81, v133
	v_mul_f32_e32 v134, v74, v74
	v_mul_f32_e32 v135, v75, v75
	v_mul_f32_e32 v136, v76, v76
	v_mul_f32_e32 v137, v77, v77
	v_fma_f32 v134, v134, v182, v183
	v_fma_f32 v135, v135, v182, v183
	v_fma_f32 v136, v136, v182, v183
	v_fma_f32 v137, v137, v182, v183
	v_mul_f32_e32 v134, v74, v134
	v_mul_f32_e32 v135, v75, v135
	v_mul_f32_e32 v136, v76, v136
	v_mul_f32_e32 v137, v77, v137
	v_exp_f32_e32 v134, v134
	v_exp_f32_e32 v135, v135
	v_exp_f32_e32 v136, v136
	v_exp_f32_e32 v137, v137
	v_add_f32_e32 v134, 1.0, v134
	v_add_f32_e32 v135, 1.0, v135
	v_add_f32_e32 v136, 1.0, v136
	v_add_f32_e32 v137, 1.0, v137
	v_rcp_f32_e32 v134, v134
	v_rcp_f32_e32 v135, v135
	v_rcp_f32_e32 v136, v136
	v_rcp_f32_e32 v137, v137
	s_nop 0
	v_mul_f32_e32 v74, v74, v134
	v_mul_f32_e32 v75, v75, v135
	v_mul_f32_e32 v76, v76, v136
	v_mul_f32_e32 v77, v77, v137
	v_mul_f32_e32 v130, v70, v70
	v_mul_f32_e32 v131, v71, v71
	v_mul_f32_e32 v132, v72, v72
	v_mul_f32_e32 v133, v73, v73
	v_fma_f32 v130, v130, v182, v183
	v_fma_f32 v131, v131, v182, v183
	v_fma_f32 v132, v132, v182, v183
	v_fma_f32 v133, v133, v182, v183
	v_mul_f32_e32 v130, v70, v130
	v_mul_f32_e32 v131, v71, v131
	v_mul_f32_e32 v132, v72, v132
	v_mul_f32_e32 v133, v73, v133
	v_exp_f32_e32 v130, v130
	v_exp_f32_e32 v131, v131
	v_exp_f32_e32 v132, v132
	v_exp_f32_e32 v133, v133
	v_add_f32_e32 v130, 1.0, v130
	v_add_f32_e32 v131, 1.0, v131
	v_add_f32_e32 v132, 1.0, v132
	v_add_f32_e32 v133, 1.0, v133
	v_rcp_f32_e32 v130, v130
	v_rcp_f32_e32 v131, v131
	v_rcp_f32_e32 v132, v132
	v_rcp_f32_e32 v133, v133
	s_nop 0
	v_mul_f32_e32 v70, v70, v130
	v_mul_f32_e32 v71, v71, v131
	v_mul_f32_e32 v72, v72, v132
	v_mul_f32_e32 v73, v73, v133
	v_mul_f32_e32 v134, v66, v66
	v_mul_f32_e32 v135, v67, v67
	v_mul_f32_e32 v136, v68, v68
	v_mul_f32_e32 v137, v69, v69
	v_fma_f32 v134, v134, v182, v183
	v_fma_f32 v135, v135, v182, v183
	v_fma_f32 v136, v136, v182, v183
	v_fma_f32 v137, v137, v182, v183
	v_mul_f32_e32 v134, v66, v134
	v_mul_f32_e32 v135, v67, v135
	v_mul_f32_e32 v136, v68, v136
	v_mul_f32_e32 v137, v69, v137
	v_exp_f32_e32 v134, v134
	v_exp_f32_e32 v135, v135
	v_exp_f32_e32 v136, v136
	v_exp_f32_e32 v137, v137
	v_add_f32_e32 v134, 1.0, v134
	v_add_f32_e32 v135, 1.0, v135
	v_add_f32_e32 v136, 1.0, v136
	v_add_f32_e32 v137, 1.0, v137
	v_rcp_f32_e32 v134, v134
	v_rcp_f32_e32 v135, v135
	v_rcp_f32_e32 v136, v136
	v_rcp_f32_e32 v137, v137
	s_nop 0
	v_mul_f32_e32 v66, v66, v134
	v_mul_f32_e32 v67, v67, v135
	v_mul_f32_e32 v68, v68, v136
	v_mul_f32_e32 v69, v69, v137
	v_pk_mul_f32 v[136:137], v[78:79], v[78:79]
	v_pk_mul_f32 v[138:139], v[80:81], v[80:81]
	v_add_f32_e32 v140, 0, v136
	v_add_f32_e32 v140, v137, v140
	v_add_f32_e32 v140, v138, v140
	v_add_f32_e32 v140, v139, v140
	v_pk_mul_f32 v[136:137], v[74:75], v[74:75]
	v_pk_mul_f32 v[138:139], v[76:77], v[76:77]
	v_add_f32_e32 v140, v136, v140
	v_add_f32_e32 v140, v137, v140
	v_add_f32_e32 v140, v138, v140
	v_add_f32_e32 v140, v139, v140
	v_pk_mul_f32 v[136:137], v[70:71], v[70:71]
	v_pk_mul_f32 v[138:139], v[72:73], v[72:73]
	v_add_f32_e32 v140, v136, v140
	v_add_f32_e32 v140, v137, v140
	v_add_f32_e32 v140, v138, v140
	v_add_f32_e32 v140, v139, v140
	v_pk_mul_f32 v[136:137], v[66:67], v[66:67]
	v_pk_mul_f32 v[138:139], v[68:69], v[68:69]
	v_add_f32_e32 v140, v136, v140
	v_add_f32_e32 v140, v137, v140
	v_add_f32_e32 v140, v138, v140
	v_add_f32_e32 v140, v139, v140
	ds_bpermute_b32 v141, v186, v140
	s_waitcnt lgkmcnt(0)
	v_add_f32_e32 v140, v140, v141
	ds_bpermute_b32 v141, v185, v140
	s_waitcnt lgkmcnt(0)
	v_add_f32_e32 v140, v140, v141
	v_mov_b32_e32 v141, 0x358637bd
	v_fmamk_f32 v140, v140, 0x3c800000, v141
	v_mul_f32_e32 v141, 0x4b800000, v140
	v_cmp_gt_f32_e32 vcc, 0x800000, v140
	s_nop 1
	v_cndmask_b32_e32 v140, v140, v141, vcc
	v_rsq_f32_e32 v140, v140
	s_nop 0
	v_mul_f32_e32 v141, 0x45800000, v140
	v_cndmask_b32_e32 v147, v140, v141, vcc
	v_mul_f32_e32 v130, v62, v62
	v_mul_f32_e32 v131, v63, v63
	v_mul_f32_e32 v132, v64, v64
	v_mul_f32_e32 v133, v65, v65
	v_fma_f32 v130, v130, v182, v183
	v_fma_f32 v131, v131, v182, v183
	v_fma_f32 v132, v132, v182, v183
	v_fma_f32 v133, v133, v182, v183
	v_mul_f32_e32 v130, v62, v130
	v_mul_f32_e32 v131, v63, v131
	v_mul_f32_e32 v132, v64, v132
	v_mul_f32_e32 v133, v65, v133
	v_exp_f32_e32 v130, v130
	v_exp_f32_e32 v131, v131
	v_exp_f32_e32 v132, v132
	v_exp_f32_e32 v133, v133
	v_add_f32_e32 v130, 1.0, v130
	v_add_f32_e32 v131, 1.0, v131
	v_add_f32_e32 v132, 1.0, v132
	v_add_f32_e32 v133, 1.0, v133
	v_rcp_f32_e32 v130, v130
	v_rcp_f32_e32 v131, v131
	v_rcp_f32_e32 v132, v132
	v_rcp_f32_e32 v133, v133
	s_nop 0
	v_mul_f32_e32 v62, v62, v130
	v_mul_f32_e32 v63, v63, v131
	v_mul_f32_e32 v64, v64, v132
	v_mul_f32_e32 v65, v65, v133
	v_mul_f32_e32 v134, v58, v58
	v_mul_f32_e32 v135, v59, v59
	v_mul_f32_e32 v136, v60, v60
	v_mul_f32_e32 v137, v61, v61
	v_fma_f32 v134, v134, v182, v183
	v_fma_f32 v135, v135, v182, v183
	v_fma_f32 v136, v136, v182, v183
	v_fma_f32 v137, v137, v182, v183
	v_mul_f32_e32 v134, v58, v134
	v_mul_f32_e32 v135, v59, v135
	v_mul_f32_e32 v136, v60, v136
	v_mul_f32_e32 v137, v61, v137
	v_exp_f32_e32 v134, v134
	v_exp_f32_e32 v135, v135
	v_exp_f32_e32 v136, v136
	v_exp_f32_e32 v137, v137
	v_add_f32_e32 v134, 1.0, v134
	v_add_f32_e32 v135, 1.0, v135
	v_add_f32_e32 v136, 1.0, v136
	v_add_f32_e32 v137, 1.0, v137
	v_rcp_f32_e32 v134, v134
	v_rcp_f32_e32 v135, v135
	v_rcp_f32_e32 v136, v136
	v_rcp_f32_e32 v137, v137
	s_nop 0
	v_mul_f32_e32 v58, v58, v134
	v_mul_f32_e32 v59, v59, v135
	v_mul_f32_e32 v60, v60, v136
	v_mul_f32_e32 v61, v61, v137
	v_mul_f32_e32 v130, v54, v54
	v_mul_f32_e32 v131, v55, v55
	v_mul_f32_e32 v132, v56, v56
	v_mul_f32_e32 v133, v57, v57
	v_fma_f32 v130, v130, v182, v183
	v_fma_f32 v131, v131, v182, v183
	v_fma_f32 v132, v132, v182, v183
	v_fma_f32 v133, v133, v182, v183
	v_mul_f32_e32 v130, v54, v130
	v_mul_f32_e32 v131, v55, v131
	v_mul_f32_e32 v132, v56, v132
	v_mul_f32_e32 v133, v57, v133
	v_exp_f32_e32 v130, v130
	v_exp_f32_e32 v131, v131
	v_exp_f32_e32 v132, v132
	v_exp_f32_e32 v133, v133
	v_add_f32_e32 v130, 1.0, v130
	v_add_f32_e32 v131, 1.0, v131
	v_add_f32_e32 v132, 1.0, v132
	v_add_f32_e32 v133, 1.0, v133
	v_rcp_f32_e32 v130, v130
	v_rcp_f32_e32 v131, v131
	v_rcp_f32_e32 v132, v132
	v_rcp_f32_e32 v133, v133
	s_nop 0
	v_mul_f32_e32 v54, v54, v130
	v_mul_f32_e32 v55, v55, v131
	v_mul_f32_e32 v56, v56, v132
	v_mul_f32_e32 v57, v57, v133
	v_mul_f32_e32 v134, v50, v50
	v_mul_f32_e32 v135, v51, v51
	v_mul_f32_e32 v136, v52, v52
	v_mul_f32_e32 v137, v53, v53
	v_fma_f32 v134, v134, v182, v183
	v_fma_f32 v135, v135, v182, v183
	v_fma_f32 v136, v136, v182, v183
	v_fma_f32 v137, v137, v182, v183
	v_mul_f32_e32 v134, v50, v134
	v_mul_f32_e32 v135, v51, v135
	v_mul_f32_e32 v136, v52, v136
	v_mul_f32_e32 v137, v53, v137
	v_exp_f32_e32 v134, v134
	v_exp_f32_e32 v135, v135
	v_exp_f32_e32 v136, v136
	v_exp_f32_e32 v137, v137
	v_add_f32_e32 v134, 1.0, v134
	v_add_f32_e32 v135, 1.0, v135
	v_add_f32_e32 v136, 1.0, v136
	v_add_f32_e32 v137, 1.0, v137
	v_rcp_f32_e32 v134, v134
	v_rcp_f32_e32 v135, v135
	v_rcp_f32_e32 v136, v136
	v_rcp_f32_e32 v137, v137
	s_nop 0
	v_mul_f32_e32 v50, v50, v134
	v_mul_f32_e32 v51, v51, v135
	v_mul_f32_e32 v52, v52, v136
	v_mul_f32_e32 v53, v53, v137
	v_pk_mul_f32 v[136:137], v[62:63], v[62:63]
	v_pk_mul_f32 v[138:139], v[64:65], v[64:65]
	v_add_f32_e32 v140, 0, v136
	v_add_f32_e32 v140, v137, v140
	v_add_f32_e32 v140, v138, v140
	v_add_f32_e32 v140, v139, v140
	v_pk_mul_f32 v[136:137], v[58:59], v[58:59]
	v_pk_mul_f32 v[138:139], v[60:61], v[60:61]
	v_add_f32_e32 v140, v136, v140
	v_add_f32_e32 v140, v137, v140
	v_add_f32_e32 v140, v138, v140
	v_add_f32_e32 v140, v139, v140
	v_pk_mul_f32 v[136:137], v[54:55], v[54:55]
	v_pk_mul_f32 v[138:139], v[56:57], v[56:57]
	v_add_f32_e32 v140, v136, v140
	v_add_f32_e32 v140, v137, v140
	v_add_f32_e32 v140, v138, v140
	v_add_f32_e32 v140, v139, v140
	v_pk_mul_f32 v[136:137], v[50:51], v[50:51]
	v_pk_mul_f32 v[138:139], v[52:53], v[52:53]
	v_add_f32_e32 v140, v136, v140
	v_add_f32_e32 v140, v137, v140
	v_add_f32_e32 v140, v138, v140
	v_add_f32_e32 v140, v139, v140
	ds_bpermute_b32 v141, v186, v140
	s_waitcnt lgkmcnt(0)
	v_add_f32_e32 v140, v140, v141
	ds_bpermute_b32 v141, v185, v140
	s_waitcnt lgkmcnt(0)
	v_add_f32_e32 v140, v140, v141
	v_mov_b32_e32 v141, 0x358637bd
	v_fmamk_f32 v140, v140, 0x3c800000, v141
	v_mul_f32_e32 v141, 0x4b800000, v140
	v_cmp_gt_f32_e32 vcc, 0x800000, v140
	s_nop 1
	v_cndmask_b32_e32 v140, v140, v141, vcc
	v_rsq_f32_e32 v140, v140
	s_nop 0
	v_mul_f32_e32 v141, 0x45800000, v140
	v_cndmask_b32_e32 v148, v140, v141, vcc
	v_mul_f32_e32 v130, v46, v46
	v_mul_f32_e32 v131, v47, v47
	v_mul_f32_e32 v132, v48, v48
	v_mul_f32_e32 v133, v49, v49
	v_fma_f32 v130, v130, v182, v183
	v_fma_f32 v131, v131, v182, v183
	v_fma_f32 v132, v132, v182, v183
	v_fma_f32 v133, v133, v182, v183
	v_mul_f32_e32 v130, v46, v130
	v_mul_f32_e32 v131, v47, v131
	v_mul_f32_e32 v132, v48, v132
	v_mul_f32_e32 v133, v49, v133
	v_exp_f32_e32 v130, v130
	v_exp_f32_e32 v131, v131
	v_exp_f32_e32 v132, v132
	v_exp_f32_e32 v133, v133
	v_add_f32_e32 v130, 1.0, v130
	v_add_f32_e32 v131, 1.0, v131
	v_add_f32_e32 v132, 1.0, v132
	v_add_f32_e32 v133, 1.0, v133
	v_rcp_f32_e32 v130, v130
	v_rcp_f32_e32 v131, v131
	v_rcp_f32_e32 v132, v132
	v_rcp_f32_e32 v133, v133
	s_nop 0
	v_mul_f32_e32 v46, v46, v130
	v_mul_f32_e32 v47, v47, v131
	v_mul_f32_e32 v48, v48, v132
	v_mul_f32_e32 v49, v49, v133
	v_mul_f32_e32 v134, v42, v42
	v_mul_f32_e32 v135, v43, v43
	v_mul_f32_e32 v136, v44, v44
	v_mul_f32_e32 v137, v45, v45
	v_fma_f32 v134, v134, v182, v183
	v_fma_f32 v135, v135, v182, v183
	v_fma_f32 v136, v136, v182, v183
	v_fma_f32 v137, v137, v182, v183
	v_mul_f32_e32 v134, v42, v134
	v_mul_f32_e32 v135, v43, v135
	v_mul_f32_e32 v136, v44, v136
	v_mul_f32_e32 v137, v45, v137
	v_exp_f32_e32 v134, v134
	v_exp_f32_e32 v135, v135
	v_exp_f32_e32 v136, v136
	v_exp_f32_e32 v137, v137
	v_add_f32_e32 v134, 1.0, v134
	v_add_f32_e32 v135, 1.0, v135
	v_add_f32_e32 v136, 1.0, v136
	v_add_f32_e32 v137, 1.0, v137
	v_rcp_f32_e32 v134, v134
	v_rcp_f32_e32 v135, v135
	v_rcp_f32_e32 v136, v136
	v_rcp_f32_e32 v137, v137
	s_nop 0
	v_mul_f32_e32 v42, v42, v134
	v_mul_f32_e32 v43, v43, v135
	v_mul_f32_e32 v44, v44, v136
	v_mul_f32_e32 v45, v45, v137
	v_mul_f32_e32 v130, v38, v38
	v_mul_f32_e32 v131, v39, v39
	v_mul_f32_e32 v132, v40, v40
	v_mul_f32_e32 v133, v41, v41
	v_fma_f32 v130, v130, v182, v183
	v_fma_f32 v131, v131, v182, v183
	v_fma_f32 v132, v132, v182, v183
	v_fma_f32 v133, v133, v182, v183
	v_mul_f32_e32 v130, v38, v130
	v_mul_f32_e32 v131, v39, v131
	v_mul_f32_e32 v132, v40, v132
	v_mul_f32_e32 v133, v41, v133
	v_exp_f32_e32 v130, v130
	v_exp_f32_e32 v131, v131
	v_exp_f32_e32 v132, v132
	v_exp_f32_e32 v133, v133
	v_add_f32_e32 v130, 1.0, v130
	v_add_f32_e32 v131, 1.0, v131
	v_add_f32_e32 v132, 1.0, v132
	v_add_f32_e32 v133, 1.0, v133
	v_rcp_f32_e32 v130, v130
	v_rcp_f32_e32 v131, v131
	v_rcp_f32_e32 v132, v132
	v_rcp_f32_e32 v133, v133
	s_nop 0
	v_mul_f32_e32 v38, v38, v130
	v_mul_f32_e32 v39, v39, v131
	v_mul_f32_e32 v40, v40, v132
	v_mul_f32_e32 v41, v41, v133
	v_mul_f32_e32 v134, v34, v34
	v_mul_f32_e32 v135, v35, v35
	v_mul_f32_e32 v136, v36, v36
	v_mul_f32_e32 v137, v37, v37
	v_fma_f32 v134, v134, v182, v183
	v_fma_f32 v135, v135, v182, v183
	v_fma_f32 v136, v136, v182, v183
	v_fma_f32 v137, v137, v182, v183
	v_mul_f32_e32 v134, v34, v134
	v_mul_f32_e32 v135, v35, v135
	v_mul_f32_e32 v136, v36, v136
	v_mul_f32_e32 v137, v37, v137
	v_exp_f32_e32 v134, v134
	v_exp_f32_e32 v135, v135
	v_exp_f32_e32 v136, v136
	v_exp_f32_e32 v137, v137
	v_add_f32_e32 v134, 1.0, v134
	v_add_f32_e32 v135, 1.0, v135
	v_add_f32_e32 v136, 1.0, v136
	v_add_f32_e32 v137, 1.0, v137
	v_rcp_f32_e32 v134, v134
	v_rcp_f32_e32 v135, v135
	v_rcp_f32_e32 v136, v136
	v_rcp_f32_e32 v137, v137
	s_nop 0
	v_mul_f32_e32 v34, v34, v134
	v_mul_f32_e32 v35, v35, v135
	v_mul_f32_e32 v36, v36, v136
	v_mul_f32_e32 v37, v37, v137
	v_pk_mul_f32 v[136:137], v[46:47], v[46:47]
	v_pk_mul_f32 v[138:139], v[48:49], v[48:49]
	v_add_f32_e32 v140, 0, v136
	v_add_f32_e32 v140, v137, v140
	v_add_f32_e32 v140, v138, v140
	v_add_f32_e32 v140, v139, v140
	v_pk_mul_f32 v[136:137], v[42:43], v[42:43]
	v_pk_mul_f32 v[138:139], v[44:45], v[44:45]
	v_add_f32_e32 v140, v136, v140
	v_add_f32_e32 v140, v137, v140
	v_add_f32_e32 v140, v138, v140
	v_add_f32_e32 v140, v139, v140
	v_pk_mul_f32 v[136:137], v[38:39], v[38:39]
	v_pk_mul_f32 v[138:139], v[40:41], v[40:41]
	v_add_f32_e32 v140, v136, v140
	v_add_f32_e32 v140, v137, v140
	v_add_f32_e32 v140, v138, v140
	v_add_f32_e32 v140, v139, v140
	v_pk_mul_f32 v[136:137], v[34:35], v[34:35]
	v_pk_mul_f32 v[138:139], v[36:37], v[36:37]
	v_add_f32_e32 v140, v136, v140
	v_add_f32_e32 v140, v137, v140
	v_add_f32_e32 v140, v138, v140
	v_add_f32_e32 v140, v139, v140
	ds_bpermute_b32 v141, v186, v140
	s_waitcnt lgkmcnt(0)
	v_add_f32_e32 v140, v140, v141
	ds_bpermute_b32 v141, v185, v140
	s_waitcnt lgkmcnt(0)
	v_add_f32_e32 v140, v140, v141
	v_mov_b32_e32 v141, 0x358637bd
	v_fmamk_f32 v140, v140, 0x3c800000, v141
	v_mul_f32_e32 v141, 0x4b800000, v140
	v_cmp_gt_f32_e32 vcc, 0x800000, v140
	s_nop 1
	v_cndmask_b32_e32 v140, v140, v141, vcc
	v_rsq_f32_e32 v140, v140
	s_nop 0
	v_mul_f32_e32 v141, 0x45800000, v140
	v_cndmask_b32_e32 v149, v140, v141, vcc
	v_mul_f32_e32 v130, v30, v30
	v_mul_f32_e32 v131, v31, v31
	v_mul_f32_e32 v132, v32, v32
	v_mul_f32_e32 v133, v33, v33
	v_fma_f32 v130, v130, v182, v183
	v_fma_f32 v131, v131, v182, v183
	v_fma_f32 v132, v132, v182, v183
	v_fma_f32 v133, v133, v182, v183
	v_mul_f32_e32 v130, v30, v130
	v_mul_f32_e32 v131, v31, v131
	v_mul_f32_e32 v132, v32, v132
	v_mul_f32_e32 v133, v33, v133
	v_exp_f32_e32 v130, v130
	v_exp_f32_e32 v131, v131
	v_exp_f32_e32 v132, v132
	v_exp_f32_e32 v133, v133
	v_add_f32_e32 v130, 1.0, v130
	v_add_f32_e32 v131, 1.0, v131
	v_add_f32_e32 v132, 1.0, v132
	v_add_f32_e32 v133, 1.0, v133
	v_rcp_f32_e32 v130, v130
	v_rcp_f32_e32 v131, v131
	v_rcp_f32_e32 v132, v132
	v_rcp_f32_e32 v133, v133
	s_nop 0
	v_mul_f32_e32 v30, v30, v130
	v_mul_f32_e32 v31, v31, v131
	v_mul_f32_e32 v32, v32, v132
	v_mul_f32_e32 v33, v33, v133
	v_mul_f32_e32 v134, v26, v26
	v_mul_f32_e32 v135, v27, v27
	v_mul_f32_e32 v136, v28, v28
	v_mul_f32_e32 v137, v29, v29
	v_fma_f32 v134, v134, v182, v183
	v_fma_f32 v135, v135, v182, v183
	v_fma_f32 v136, v136, v182, v183
	v_fma_f32 v137, v137, v182, v183
	v_mul_f32_e32 v134, v26, v134
	v_mul_f32_e32 v135, v27, v135
	v_mul_f32_e32 v136, v28, v136
	v_mul_f32_e32 v137, v29, v137
	v_exp_f32_e32 v134, v134
	v_exp_f32_e32 v135, v135
	v_exp_f32_e32 v136, v136
	v_exp_f32_e32 v137, v137
	v_add_f32_e32 v134, 1.0, v134
	v_add_f32_e32 v135, 1.0, v135
	v_add_f32_e32 v136, 1.0, v136
	v_add_f32_e32 v137, 1.0, v137
	v_rcp_f32_e32 v134, v134
	v_rcp_f32_e32 v135, v135
	v_rcp_f32_e32 v136, v136
	v_rcp_f32_e32 v137, v137
	s_nop 0
	v_mul_f32_e32 v26, v26, v134
	v_mul_f32_e32 v27, v27, v135
	v_mul_f32_e32 v28, v28, v136
	v_mul_f32_e32 v29, v29, v137
	v_mul_f32_e32 v130, v22, v22
	v_mul_f32_e32 v131, v23, v23
	v_mul_f32_e32 v132, v24, v24
	v_mul_f32_e32 v133, v25, v25
	v_fma_f32 v130, v130, v182, v183
	v_fma_f32 v131, v131, v182, v183
	v_fma_f32 v132, v132, v182, v183
	v_fma_f32 v133, v133, v182, v183
	v_mul_f32_e32 v130, v22, v130
	v_mul_f32_e32 v131, v23, v131
	v_mul_f32_e32 v132, v24, v132
	v_mul_f32_e32 v133, v25, v133
	v_exp_f32_e32 v130, v130
	v_exp_f32_e32 v131, v131
	v_exp_f32_e32 v132, v132
	v_exp_f32_e32 v133, v133
	v_add_f32_e32 v130, 1.0, v130
	v_add_f32_e32 v131, 1.0, v131
	v_add_f32_e32 v132, 1.0, v132
	v_add_f32_e32 v133, 1.0, v133
	v_rcp_f32_e32 v130, v130
	v_rcp_f32_e32 v131, v131
	v_rcp_f32_e32 v132, v132
	v_rcp_f32_e32 v133, v133
	s_nop 0
	v_mul_f32_e32 v22, v22, v130
	v_mul_f32_e32 v23, v23, v131
	v_mul_f32_e32 v24, v24, v132
	v_mul_f32_e32 v25, v25, v133
	v_mul_f32_e32 v134, v18, v18
	v_mul_f32_e32 v135, v19, v19
	v_mul_f32_e32 v136, v20, v20
	v_mul_f32_e32 v137, v21, v21
	v_fma_f32 v134, v134, v182, v183
	v_fma_f32 v135, v135, v182, v183
	v_fma_f32 v136, v136, v182, v183
	v_fma_f32 v137, v137, v182, v183
	v_mul_f32_e32 v134, v18, v134
	v_mul_f32_e32 v135, v19, v135
	v_mul_f32_e32 v136, v20, v136
	v_mul_f32_e32 v137, v21, v137
	v_exp_f32_e32 v134, v134
	v_exp_f32_e32 v135, v135
	v_exp_f32_e32 v136, v136
	v_exp_f32_e32 v137, v137
	v_add_f32_e32 v134, 1.0, v134
	v_add_f32_e32 v135, 1.0, v135
	v_add_f32_e32 v136, 1.0, v136
	v_add_f32_e32 v137, 1.0, v137
	v_rcp_f32_e32 v134, v134
	v_rcp_f32_e32 v135, v135
	v_rcp_f32_e32 v136, v136
	v_rcp_f32_e32 v137, v137
	s_nop 0
	v_mul_f32_e32 v18, v18, v134
	v_mul_f32_e32 v19, v19, v135
	v_mul_f32_e32 v20, v20, v136
	v_mul_f32_e32 v21, v21, v137
	v_pk_mul_f32 v[136:137], v[30:31], v[30:31]
	v_pk_mul_f32 v[138:139], v[32:33], v[32:33]
	v_add_f32_e32 v140, 0, v136
	v_add_f32_e32 v140, v137, v140
	v_add_f32_e32 v140, v138, v140
	v_add_f32_e32 v140, v139, v140
	v_pk_mul_f32 v[136:137], v[26:27], v[26:27]
	v_pk_mul_f32 v[138:139], v[28:29], v[28:29]
	v_add_f32_e32 v140, v136, v140
	v_add_f32_e32 v140, v137, v140
	v_add_f32_e32 v140, v138, v140
	v_add_f32_e32 v140, v139, v140
	v_pk_mul_f32 v[136:137], v[22:23], v[22:23]
	v_pk_mul_f32 v[138:139], v[24:25], v[24:25]
	v_add_f32_e32 v140, v136, v140
	v_add_f32_e32 v140, v137, v140
	v_add_f32_e32 v140, v138, v140
	v_add_f32_e32 v140, v139, v140
	v_pk_mul_f32 v[136:137], v[18:19], v[18:19]
	v_pk_mul_f32 v[138:139], v[20:21], v[20:21]
	v_add_f32_e32 v140, v136, v140
	v_add_f32_e32 v140, v137, v140
	v_add_f32_e32 v140, v138, v140
	v_add_f32_e32 v140, v139, v140
	ds_bpermute_b32 v141, v186, v140
	s_waitcnt lgkmcnt(0)
	v_add_f32_e32 v140, v140, v141
	ds_bpermute_b32 v141, v185, v140
	s_waitcnt lgkmcnt(0)
	v_add_f32_e32 v140, v140, v141
	v_mov_b32_e32 v141, 0x358637bd
	v_fmamk_f32 v140, v140, 0x3c800000, v141
	v_mul_f32_e32 v141, 0x4b800000, v140
	v_cmp_gt_f32_e32 vcc, 0x800000, v140
	s_nop 1
	v_cndmask_b32_e32 v140, v140, v141, vcc
	v_rsq_f32_e32 v140, v140
	s_nop 0
	v_mul_f32_e32 v141, 0x45800000, v140
	v_cndmask_b32_e32 v150, v140, v141, vcc
	v_mul_f32_e32 v130, v14, v14
	v_mul_f32_e32 v131, v15, v15
	v_mul_f32_e32 v132, v16, v16
	v_mul_f32_e32 v133, v17, v17
	v_fma_f32 v130, v130, v182, v183
	v_fma_f32 v131, v131, v182, v183
	v_fma_f32 v132, v132, v182, v183
	v_fma_f32 v133, v133, v182, v183
	v_mul_f32_e32 v130, v14, v130
	v_mul_f32_e32 v131, v15, v131
	v_mul_f32_e32 v132, v16, v132
	v_mul_f32_e32 v133, v17, v133
	v_exp_f32_e32 v130, v130
	v_exp_f32_e32 v131, v131
	v_exp_f32_e32 v132, v132
	v_exp_f32_e32 v133, v133
	v_add_f32_e32 v130, 1.0, v130
	v_add_f32_e32 v131, 1.0, v131
	v_add_f32_e32 v132, 1.0, v132
	v_add_f32_e32 v133, 1.0, v133
	v_rcp_f32_e32 v130, v130
	v_rcp_f32_e32 v131, v131
	v_rcp_f32_e32 v132, v132
	v_rcp_f32_e32 v133, v133
	s_nop 0
	v_mul_f32_e32 v14, v14, v130
	v_mul_f32_e32 v15, v15, v131
	v_mul_f32_e32 v16, v16, v132
	v_mul_f32_e32 v17, v17, v133
	v_mul_f32_e32 v134, v10, v10
	v_mul_f32_e32 v135, v11, v11
	v_mul_f32_e32 v136, v12, v12
	v_mul_f32_e32 v137, v13, v13
	v_fma_f32 v134, v134, v182, v183
	v_fma_f32 v135, v135, v182, v183
	v_fma_f32 v136, v136, v182, v183
	v_fma_f32 v137, v137, v182, v183
	v_mul_f32_e32 v134, v10, v134
	v_mul_f32_e32 v135, v11, v135
	v_mul_f32_e32 v136, v12, v136
	v_mul_f32_e32 v137, v13, v137
	v_exp_f32_e32 v134, v134
	v_exp_f32_e32 v135, v135
	v_exp_f32_e32 v136, v136
	v_exp_f32_e32 v137, v137
	v_add_f32_e32 v134, 1.0, v134
	v_add_f32_e32 v135, 1.0, v135
	v_add_f32_e32 v136, 1.0, v136
	v_add_f32_e32 v137, 1.0, v137
	v_rcp_f32_e32 v134, v134
	v_rcp_f32_e32 v135, v135
	v_rcp_f32_e32 v136, v136
	v_rcp_f32_e32 v137, v137
	s_nop 0
	v_mul_f32_e32 v10, v10, v134
	v_mul_f32_e32 v11, v11, v135
	v_mul_f32_e32 v12, v12, v136
	v_mul_f32_e32 v13, v13, v137
	v_mul_f32_e32 v130, v6, v6
	v_mul_f32_e32 v131, v7, v7
	v_mul_f32_e32 v132, v8, v8
	v_mul_f32_e32 v133, v9, v9
	v_fma_f32 v130, v130, v182, v183
	v_fma_f32 v131, v131, v182, v183
	v_fma_f32 v132, v132, v182, v183
	v_fma_f32 v133, v133, v182, v183
	v_mul_f32_e32 v130, v6, v130
	v_mul_f32_e32 v131, v7, v131
	v_mul_f32_e32 v132, v8, v132
	v_mul_f32_e32 v133, v9, v133
	v_exp_f32_e32 v130, v130
	v_exp_f32_e32 v131, v131
	v_exp_f32_e32 v132, v132
	v_exp_f32_e32 v133, v133
	v_add_f32_e32 v130, 1.0, v130
	v_add_f32_e32 v131, 1.0, v131
	v_add_f32_e32 v132, 1.0, v132
	v_add_f32_e32 v133, 1.0, v133
	v_rcp_f32_e32 v130, v130
	v_rcp_f32_e32 v131, v131
	v_rcp_f32_e32 v132, v132
	v_rcp_f32_e32 v133, v133
	s_nop 0
	v_mul_f32_e32 v6, v6, v130
	v_mul_f32_e32 v7, v7, v131
	v_mul_f32_e32 v8, v8, v132
	v_mul_f32_e32 v9, v9, v133
	v_mul_f32_e32 v134, v2, v2
	v_mul_f32_e32 v135, v3, v3
	v_mul_f32_e32 v136, v4, v4
	v_mul_f32_e32 v137, v5, v5
	v_fma_f32 v134, v134, v182, v183
	v_fma_f32 v135, v135, v182, v183
	v_fma_f32 v136, v136, v182, v183
	v_fma_f32 v137, v137, v182, v183
	v_mul_f32_e32 v134, v2, v134
	v_mul_f32_e32 v135, v3, v135
	v_mul_f32_e32 v136, v4, v136
	v_mul_f32_e32 v137, v5, v137
	v_exp_f32_e32 v134, v134
	v_exp_f32_e32 v135, v135
	v_exp_f32_e32 v136, v136
	v_exp_f32_e32 v137, v137
	v_add_f32_e32 v134, 1.0, v134
	v_add_f32_e32 v135, 1.0, v135
	v_add_f32_e32 v136, 1.0, v136
	v_add_f32_e32 v137, 1.0, v137
	v_rcp_f32_e32 v134, v134
	v_rcp_f32_e32 v135, v135
	v_rcp_f32_e32 v136, v136
	v_rcp_f32_e32 v137, v137
	s_nop 0
	v_mul_f32_e32 v2, v2, v134
	v_mul_f32_e32 v3, v3, v135
	v_mul_f32_e32 v4, v4, v136
	v_mul_f32_e32 v5, v5, v137
	v_pk_mul_f32 v[136:137], v[14:15], v[14:15]
	v_pk_mul_f32 v[138:139], v[16:17], v[16:17]
	v_add_f32_e32 v140, 0, v136
	v_add_f32_e32 v140, v137, v140
	v_add_f32_e32 v140, v138, v140
	v_add_f32_e32 v140, v139, v140
	v_pk_mul_f32 v[136:137], v[10:11], v[10:11]
	v_pk_mul_f32 v[138:139], v[12:13], v[12:13]
	v_add_f32_e32 v140, v136, v140
	v_add_f32_e32 v140, v137, v140
	v_add_f32_e32 v140, v138, v140
	v_add_f32_e32 v140, v139, v140
	v_pk_mul_f32 v[136:137], v[6:7], v[6:7]
	v_pk_mul_f32 v[138:139], v[8:9], v[8:9]
	v_add_f32_e32 v140, v136, v140
	v_add_f32_e32 v140, v137, v140
	v_add_f32_e32 v140, v138, v140
	v_add_f32_e32 v140, v139, v140
	v_pk_mul_f32 v[136:137], v[2:3], v[2:3]
	v_pk_mul_f32 v[138:139], v[4:5], v[4:5]
	v_add_f32_e32 v140, v136, v140
	v_add_f32_e32 v140, v137, v140
	v_add_f32_e32 v140, v138, v140
	v_add_f32_e32 v140, v139, v140
	ds_bpermute_b32 v141, v186, v140
	s_waitcnt lgkmcnt(0)
	v_add_f32_e32 v140, v140, v141
	ds_bpermute_b32 v141, v185, v140
	s_waitcnt lgkmcnt(0)
	v_add_f32_e32 v140, v140, v141
	v_mov_b32_e32 v141, 0x358637bd
	v_fmamk_f32 v140, v140, 0x3c800000, v141
	v_mul_f32_e32 v141, 0x4b800000, v140
	v_cmp_gt_f32_e32 vcc, 0x800000, v140
	s_nop 1
	v_cndmask_b32_e32 v140, v140, v141, vcc
	v_rsq_f32_e32 v140, v140
	s_nop 0
	v_mul_f32_e32 v141, 0x45800000, v140
	v_cndmask_b32_e32 v151, v140, v141, vcc
	v_fma_mixlo_f16 v130, v126, v144, 0
	v_fma_mixhi_f16 v130, v127, v144, 0
	ds_write_b16 v187, v130 offset:0
	ds_write_b16_d16_hi v187, v130 offset:144
	v_fma_mixlo_f16 v131, v128, v144, 0
	v_fma_mixhi_f16 v131, v129, v144, 0
	ds_write_b16 v187, v131 offset:288
	ds_write_b16_d16_hi v187, v131 offset:432
	v_fma_mixlo_f16 v132, v122, v144, 0
	v_fma_mixhi_f16 v132, v123, v144, 0
	ds_write_b16 v187, v132 offset:2304
	ds_write_b16_d16_hi v187, v132 offset:2448
	v_fma_mixlo_f16 v133, v124, v144, 0
	v_fma_mixhi_f16 v133, v125, v144, 0
	ds_write_b16 v187, v133 offset:2592
	ds_write_b16_d16_hi v187, v133 offset:2736
	v_fma_mixlo_f16 v134, v118, v144, 0
	v_fma_mixhi_f16 v134, v119, v144, 0
	ds_write_b16 v187, v134 offset:4608
	ds_write_b16_d16_hi v187, v134 offset:4752
	v_fma_mixlo_f16 v135, v120, v144, 0
	v_fma_mixhi_f16 v135, v121, v144, 0
	ds_write_b16 v187, v135 offset:4896
	ds_write_b16_d16_hi v187, v135 offset:5040
	v_fma_mixlo_f16 v136, v114, v144, 0
	v_fma_mixhi_f16 v136, v115, v144, 0
	ds_write_b16 v187, v136 offset:6912
	ds_write_b16_d16_hi v187, v136 offset:7056
	v_fma_mixlo_f16 v137, v116, v144, 0
	v_fma_mixhi_f16 v137, v117, v144, 0
	ds_write_b16 v187, v137 offset:7200
	ds_write_b16_d16_hi v187, v137 offset:7344
	v_fma_mixlo_f16 v130, v110, v145, 0
	v_fma_mixhi_f16 v130, v111, v145, 0
	ds_write_b16 v187, v130 offset:32
	ds_write_b16_d16_hi v187, v130 offset:176
	v_fma_mixlo_f16 v131, v112, v145, 0
	v_fma_mixhi_f16 v131, v113, v145, 0
	ds_write_b16 v187, v131 offset:320
	ds_write_b16_d16_hi v187, v131 offset:464
	v_fma_mixlo_f16 v132, v106, v145, 0
	v_fma_mixhi_f16 v132, v107, v145, 0
	ds_write_b16 v187, v132 offset:2336
	ds_write_b16_d16_hi v187, v132 offset:2480
	v_fma_mixlo_f16 v133, v108, v145, 0
	v_fma_mixhi_f16 v133, v109, v145, 0
	ds_write_b16 v187, v133 offset:2624
	ds_write_b16_d16_hi v187, v133 offset:2768
	v_fma_mixlo_f16 v134, v102, v145, 0
	v_fma_mixhi_f16 v134, v103, v145, 0
	ds_write_b16 v187, v134 offset:4640
	ds_write_b16_d16_hi v187, v134 offset:4784
	v_fma_mixlo_f16 v135, v104, v145, 0
	v_fma_mixhi_f16 v135, v105, v145, 0
	ds_write_b16 v187, v135 offset:4928
	ds_write_b16_d16_hi v187, v135 offset:5072
	v_fma_mixlo_f16 v136, v98, v145, 0
	v_fma_mixhi_f16 v136, v99, v145, 0
	ds_write_b16 v187, v136 offset:6944
	ds_write_b16_d16_hi v187, v136 offset:7088
	v_fma_mixlo_f16 v137, v100, v145, 0
	v_fma_mixhi_f16 v137, v101, v145, 0
	ds_write_b16 v187, v137 offset:7232
	ds_write_b16_d16_hi v187, v137 offset:7376
	v_fma_mixlo_f16 v130, v94, v146, 0
	v_fma_mixhi_f16 v130, v95, v146, 0
	ds_write_b16 v187, v130 offset:64
	ds_write_b16_d16_hi v187, v130 offset:208
	v_fma_mixlo_f16 v131, v96, v146, 0
	v_fma_mixhi_f16 v131, v97, v146, 0
	ds_write_b16 v187, v131 offset:352
	ds_write_b16_d16_hi v187, v131 offset:496
	v_fma_mixlo_f16 v132, v90, v146, 0
	v_fma_mixhi_f16 v132, v91, v146, 0
	ds_write_b16 v187, v132 offset:2368
	ds_write_b16_d16_hi v187, v132 offset:2512
	v_fma_mixlo_f16 v133, v92, v146, 0
	v_fma_mixhi_f16 v133, v93, v146, 0
	ds_write_b16 v187, v133 offset:2656
	ds_write_b16_d16_hi v187, v133 offset:2800
	v_fma_mixlo_f16 v134, v86, v146, 0
	v_fma_mixhi_f16 v134, v87, v146, 0
	ds_write_b16 v187, v134 offset:4672
	ds_write_b16_d16_hi v187, v134 offset:4816
	v_fma_mixlo_f16 v135, v88, v146, 0
	v_fma_mixhi_f16 v135, v89, v146, 0
	ds_write_b16 v187, v135 offset:4960
	ds_write_b16_d16_hi v187, v135 offset:5104
	v_fma_mixlo_f16 v136, v82, v146, 0
	v_fma_mixhi_f16 v136, v83, v146, 0
	ds_write_b16 v187, v136 offset:6976
	ds_write_b16_d16_hi v187, v136 offset:7120
	v_fma_mixlo_f16 v137, v84, v146, 0
	v_fma_mixhi_f16 v137, v85, v146, 0
	ds_write_b16 v187, v137 offset:7264
	ds_write_b16_d16_hi v187, v137 offset:7408
	v_fma_mixlo_f16 v130, v78, v147, 0
	v_fma_mixhi_f16 v130, v79, v147, 0
	ds_write_b16 v187, v130 offset:96
	ds_write_b16_d16_hi v187, v130 offset:240
	v_fma_mixlo_f16 v131, v80, v147, 0
	v_fma_mixhi_f16 v131, v81, v147, 0
	ds_write_b16 v187, v131 offset:384
	ds_write_b16_d16_hi v187, v131 offset:528
	v_fma_mixlo_f16 v132, v74, v147, 0
	v_fma_mixhi_f16 v132, v75, v147, 0
	ds_write_b16 v187, v132 offset:2400
	ds_write_b16_d16_hi v187, v132 offset:2544
	v_fma_mixlo_f16 v133, v76, v147, 0
	v_fma_mixhi_f16 v133, v77, v147, 0
	ds_write_b16 v187, v133 offset:2688
	ds_write_b16_d16_hi v187, v133 offset:2832
	v_fma_mixlo_f16 v134, v70, v147, 0
	v_fma_mixhi_f16 v134, v71, v147, 0
	ds_write_b16 v187, v134 offset:4704
	ds_write_b16_d16_hi v187, v134 offset:4848
	v_fma_mixlo_f16 v135, v72, v147, 0
	v_fma_mixhi_f16 v135, v73, v147, 0
	ds_write_b16 v187, v135 offset:4992
	ds_write_b16_d16_hi v187, v135 offset:5136
	v_fma_mixlo_f16 v136, v66, v147, 0
	v_fma_mixhi_f16 v136, v67, v147, 0
	ds_write_b16 v187, v136 offset:7008
	ds_write_b16_d16_hi v187, v136 offset:7152
	v_fma_mixlo_f16 v137, v68, v147, 0
	v_fma_mixhi_f16 v137, v69, v147, 0
	ds_write_b16 v187, v137 offset:7296
	ds_write_b16_d16_hi v187, v137 offset:7440
	s_waitcnt lgkmcnt(0)
	ds_read_b128 v[152:155], v189 offset:0
	ds_read_b128 v[156:159], v189 offset:1152
	ds_read_b128 v[160:163], v189 offset:2304
	ds_read_b128 v[164:167], v189 offset:3456
	ds_read_b128 v[168:171], v189 offset:4608
	ds_read_b128 v[172:175], v189 offset:5760
	ds_read_b128 v[176:179], v189 offset:6912
	ds_read_b128 v[180:183], v189 offset:8064
	s_waitcnt lgkmcnt(7)
	global_store_dwordx4 v193, v[152:155], s[22:23]
	v_add_u32_e32 v193, s3, v193
	s_waitcnt lgkmcnt(6)
	global_store_dwordx4 v193, v[156:159], s[22:23]
	v_add_u32_e32 v193, s3, v193
	s_waitcnt lgkmcnt(5)
	global_store_dwordx4 v193, v[160:163], s[22:23]
	v_add_u32_e32 v193, s3, v193
	s_waitcnt lgkmcnt(4)
	global_store_dwordx4 v193, v[164:167], s[22:23]
	v_add_u32_e32 v193, s3, v193
	s_waitcnt lgkmcnt(3)
	global_store_dwordx4 v193, v[168:171], s[22:23]
	v_add_u32_e32 v193, s3, v193
	s_waitcnt lgkmcnt(2)
	global_store_dwordx4 v193, v[172:175], s[22:23]
	v_add_u32_e32 v193, s3, v193
	s_waitcnt lgkmcnt(1)
	global_store_dwordx4 v193, v[176:179], s[22:23]
	v_add_u32_e32 v193, s3, v193
	s_waitcnt lgkmcnt(0)
	global_store_dwordx4 v193, v[180:183], s[22:23]
	s_lshl_b32 s2, s3, 3
	s_sub_i32 s2, 0x80, s2
	s_add_i32 s2, s2, s3
	v_add_u32_e32 v193, s2, v193
	v_fma_mixlo_f16 v130, v62, v148, 0
	v_fma_mixhi_f16 v130, v63, v148, 0
	ds_write_b16 v187, v130 offset:0
	ds_write_b16_d16_hi v187, v130 offset:144
	v_fma_mixlo_f16 v131, v64, v148, 0
	v_fma_mixhi_f16 v131, v65, v148, 0
	ds_write_b16 v187, v131 offset:288
	ds_write_b16_d16_hi v187, v131 offset:432
	v_fma_mixlo_f16 v132, v58, v148, 0
	v_fma_mixhi_f16 v132, v59, v148, 0
	ds_write_b16 v187, v132 offset:2304
	ds_write_b16_d16_hi v187, v132 offset:2448
	v_fma_mixlo_f16 v133, v60, v148, 0
	v_fma_mixhi_f16 v133, v61, v148, 0
	ds_write_b16 v187, v133 offset:2592
	ds_write_b16_d16_hi v187, v133 offset:2736
	v_fma_mixlo_f16 v134, v54, v148, 0
	v_fma_mixhi_f16 v134, v55, v148, 0
	ds_write_b16 v187, v134 offset:4608
	ds_write_b16_d16_hi v187, v134 offset:4752
	v_fma_mixlo_f16 v135, v56, v148, 0
	v_fma_mixhi_f16 v135, v57, v148, 0
	ds_write_b16 v187, v135 offset:4896
	ds_write_b16_d16_hi v187, v135 offset:5040
	v_fma_mixlo_f16 v136, v50, v148, 0
	v_fma_mixhi_f16 v136, v51, v148, 0
	ds_write_b16 v187, v136 offset:6912
	ds_write_b16_d16_hi v187, v136 offset:7056
	v_fma_mixlo_f16 v137, v52, v148, 0
	v_fma_mixhi_f16 v137, v53, v148, 0
	ds_write_b16 v187, v137 offset:7200
	ds_write_b16_d16_hi v187, v137 offset:7344
	v_fma_mixlo_f16 v130, v46, v149, 0
	v_fma_mixhi_f16 v130, v47, v149, 0
	ds_write_b16 v187, v130 offset:32
	ds_write_b16_d16_hi v187, v130 offset:176
	v_fma_mixlo_f16 v131, v48, v149, 0
	v_fma_mixhi_f16 v131, v49, v149, 0
	ds_write_b16 v187, v131 offset:320
	ds_write_b16_d16_hi v187, v131 offset:464
	v_fma_mixlo_f16 v132, v42, v149, 0
	v_fma_mixhi_f16 v132, v43, v149, 0
	ds_write_b16 v187, v132 offset:2336
	ds_write_b16_d16_hi v187, v132 offset:2480
	v_fma_mixlo_f16 v133, v44, v149, 0
	v_fma_mixhi_f16 v133, v45, v149, 0
	ds_write_b16 v187, v133 offset:2624
	ds_write_b16_d16_hi v187, v133 offset:2768
	v_fma_mixlo_f16 v134, v38, v149, 0
	v_fma_mixhi_f16 v134, v39, v149, 0
	ds_write_b16 v187, v134 offset:4640
	ds_write_b16_d16_hi v187, v134 offset:4784
	v_fma_mixlo_f16 v135, v40, v149, 0
	v_fma_mixhi_f16 v135, v41, v149, 0
	ds_write_b16 v187, v135 offset:4928
	ds_write_b16_d16_hi v187, v135 offset:5072
	v_fma_mixlo_f16 v136, v34, v149, 0
	v_fma_mixhi_f16 v136, v35, v149, 0
	ds_write_b16 v187, v136 offset:6944
	ds_write_b16_d16_hi v187, v136 offset:7088
	v_fma_mixlo_f16 v137, v36, v149, 0
	v_fma_mixhi_f16 v137, v37, v149, 0
	ds_write_b16 v187, v137 offset:7232
	ds_write_b16_d16_hi v187, v137 offset:7376
	v_fma_mixlo_f16 v130, v30, v150, 0
	v_fma_mixhi_f16 v130, v31, v150, 0
	ds_write_b16 v187, v130 offset:64
	ds_write_b16_d16_hi v187, v130 offset:208
	v_fma_mixlo_f16 v131, v32, v150, 0
	v_fma_mixhi_f16 v131, v33, v150, 0
	ds_write_b16 v187, v131 offset:352
	ds_write_b16_d16_hi v187, v131 offset:496
	v_fma_mixlo_f16 v132, v26, v150, 0
	v_fma_mixhi_f16 v132, v27, v150, 0
	ds_write_b16 v187, v132 offset:2368
	ds_write_b16_d16_hi v187, v132 offset:2512
	v_fma_mixlo_f16 v133, v28, v150, 0
	v_fma_mixhi_f16 v133, v29, v150, 0
	ds_write_b16 v187, v133 offset:2656
	ds_write_b16_d16_hi v187, v133 offset:2800
	v_fma_mixlo_f16 v134, v22, v150, 0
	v_fma_mixhi_f16 v134, v23, v150, 0
	ds_write_b16 v187, v134 offset:4672
	ds_write_b16_d16_hi v187, v134 offset:4816
	v_fma_mixlo_f16 v135, v24, v150, 0
	v_fma_mixhi_f16 v135, v25, v150, 0
	ds_write_b16 v187, v135 offset:4960
	ds_write_b16_d16_hi v187, v135 offset:5104
	v_fma_mixlo_f16 v136, v18, v150, 0
	v_fma_mixhi_f16 v136, v19, v150, 0
	ds_write_b16 v187, v136 offset:6976
	ds_write_b16_d16_hi v187, v136 offset:7120
	v_fma_mixlo_f16 v137, v20, v150, 0
	v_fma_mixhi_f16 v137, v21, v150, 0
	ds_write_b16 v187, v137 offset:7264
	ds_write_b16_d16_hi v187, v137 offset:7408
	v_fma_mixlo_f16 v130, v14, v151, 0
	v_fma_mixhi_f16 v130, v15, v151, 0
	ds_write_b16 v187, v130 offset:96
	ds_write_b16_d16_hi v187, v130 offset:240
	v_fma_mixlo_f16 v131, v16, v151, 0
	v_fma_mixhi_f16 v131, v17, v151, 0
	ds_write_b16 v187, v131 offset:384
	ds_write_b16_d16_hi v187, v131 offset:528
	v_fma_mixlo_f16 v132, v10, v151, 0
	v_fma_mixhi_f16 v132, v11, v151, 0
	ds_write_b16 v187, v132 offset:2400
	ds_write_b16_d16_hi v187, v132 offset:2544
	v_fma_mixlo_f16 v133, v12, v151, 0
	v_fma_mixhi_f16 v133, v13, v151, 0
	ds_write_b16 v187, v133 offset:2688
	ds_write_b16_d16_hi v187, v133 offset:2832
	v_fma_mixlo_f16 v134, v6, v151, 0
	v_fma_mixhi_f16 v134, v7, v151, 0
	ds_write_b16 v187, v134 offset:4704
	ds_write_b16_d16_hi v187, v134 offset:4848
	v_fma_mixlo_f16 v135, v8, v151, 0
	v_fma_mixhi_f16 v135, v9, v151, 0
	ds_write_b16 v187, v135 offset:4992
	ds_write_b16_d16_hi v187, v135 offset:5136
	v_fma_mixlo_f16 v136, v2, v151, 0
	v_fma_mixhi_f16 v136, v3, v151, 0
	ds_write_b16 v187, v136 offset:7008
	ds_write_b16_d16_hi v187, v136 offset:7152
	v_fma_mixlo_f16 v137, v4, v151, 0
	v_fma_mixhi_f16 v137, v5, v151, 0
	ds_write_b16 v187, v137 offset:7296
	ds_write_b16_d16_hi v187, v137 offset:7440
	s_waitcnt lgkmcnt(0)
	ds_read_b128 v[152:155], v189 offset:0
	ds_read_b128 v[156:159], v189 offset:1152
	ds_read_b128 v[160:163], v189 offset:2304
	ds_read_b128 v[164:167], v189 offset:3456
	ds_read_b128 v[168:171], v189 offset:4608
	ds_read_b128 v[172:175], v189 offset:5760
	ds_read_b128 v[176:179], v189 offset:6912
	ds_read_b128 v[180:183], v189 offset:8064
	s_waitcnt lgkmcnt(7)
	global_store_dwordx4 v193, v[152:155], s[22:23]
	v_add_u32_e32 v193, s3, v193
	s_waitcnt lgkmcnt(6)
	global_store_dwordx4 v193, v[156:159], s[22:23]
	v_add_u32_e32 v193, s3, v193
	s_waitcnt lgkmcnt(5)
	global_store_dwordx4 v193, v[160:163], s[22:23]
	v_add_u32_e32 v193, s3, v193
	s_waitcnt lgkmcnt(4)
	global_store_dwordx4 v193, v[164:167], s[22:23]
	v_add_u32_e32 v193, s3, v193
	s_waitcnt lgkmcnt(3)
	global_store_dwordx4 v193, v[168:171], s[22:23]
	v_add_u32_e32 v193, s3, v193
	s_waitcnt lgkmcnt(2)
	global_store_dwordx4 v193, v[172:175], s[22:23]
	v_add_u32_e32 v193, s3, v193
	s_waitcnt lgkmcnt(1)
	global_store_dwordx4 v193, v[176:179], s[22:23]
	v_add_u32_e32 v193, s3, v193
	s_waitcnt lgkmcnt(0)
	global_store_dwordx4 v193, v[180:183], s[22:23]
	s_waitcnt vmcnt(16)
	s_branch .Lp1_join

.Lp1_e_gelu:
	v_and_b32_e32 v194, 15, v222
	v_bfe_u32 v195, v222, 4, 2
	v_bfe_u32 v196, v222, 6, 2
	v_lshrrev_b32_e32 v197, 8, v222
	v_lshl_or_b32 v198, v197, 7, v194
	v_lshlrev_b32_e32 v199, 2, v195
	v_lshl_or_b32 v199, v196, 6, v199
	v_readlane_b32 s22, v254, 14
	v_readlane_b32 s23, v254, 15
	s_nop 3
	s_add_u32 s22, s22, 0x98ae500
	s_addc_u32 s23, s23, 0
	s_lshl_b32 s2, s4, 17
	s_add_u32 s22, s22, s2
	s_addc_u32 s23, s23, 0
	v_lshlrev_b32_e32 v193, 9, v198
	v_lshl_add_u32 v193, v199, 1, v193
	s_add_i32 s2, s53, s95
	s_cmp_lt_i32 s2, s9
	s_cselect_b32 s21, 1, 0
	s_cselect_b32 s53, s2, s53
	s_lshr_b32 s2, s53, 5
	s_mul_hi_u32 s2, s2, 0xcccccccd
	s_lshr_b32 s2, s2, 2
	s_lshl_b32 s3, s2, 4
	s_mul_i32 s2, s2, 0xa0
	s_sub_i32 s2, s53, s2
	s_lshr_b32 s2, s2, 4
	s_and_b32 s6, s53, 15
	s_add_i32 s3, s3, s6
	s_sub_i32 s28, s53, s58
	s_lshr_b32 s28, s28, 4
	s_add_i32 s28, s28, 8
	s_or_b32 s6, s6, 0x80
	s_cmp_ge_i32 s53, s58
	s_cselect_b32 s6, s6, s3
	s_cselect_b32 s28, s28, s2
	s_lshl_b32 s2, s6, 19
	s_add_u32 s12, s64, s2
	s_addc_u32 s13, s65, 0
	s_lshl_b32 s2, s28, 19
	s_add_u32 s14, s34, s2
	s_addc_u32 s15, s35, 0
	s_mov_b32 m0, s18
	s_nop 0
	global_load_lds_dwordx4 v1, s[12:13]
	s_add_i32 m0, s18, 0x2000
	s_add_u32 s16, s12, 0x20000
	s_addc_u32 s17, s13, 0
	global_load_lds_dwordx4 v1, s[16:17]
	s_add_i32 m0, s18, 0x4000
	s_add_u32 s16, s12, 0x40000
	s_addc_u32 s17, s13, 0
	global_load_lds_dwordx4 v1, s[16:17]
	s_add_i32 m0, s18, 0x6000
	s_add_u32 s16, s12, 0x60000
	s_addc_u32 s17, s13, 0
	global_load_lds_dwordx4 v1, s[16:17]
	s_add_i32 m0, s18, 0x8000
	s_nop 0
	global_load_lds_dwordx4 v1, s[14:15]
	s_add_i32 m0, s18, 0xa000
	s_add_u32 s16, s14, 0x20000
	s_addc_u32 s17, s15, 0
	global_load_lds_dwordx4 v1, s[16:17]
	s_add_i32 m0, s18, 0xc000
	s_add_u32 s16, s14, 0x40000
	s_addc_u32 s17, s15, 0
	global_load_lds_dwordx4 v1, s[16:17]
	s_add_i32 m0, s18, 0xe000
	s_add_u32 s16, s14, 0x60000
	s_addc_u32 s17, s15, 0
	global_load_lds_dwordx4 v1, s[16:17]
	v_mov_b32_e32 v182, 0xbdd2d3e8
	v_mov_b32_e32 v183, 0xc0135761
	v_mul_f32_e32 v130, v126, v126
	v_mul_f32_e32 v131, v127, v127
	v_mul_f32_e32 v132, v128, v128
	v_mul_f32_e32 v133, v129, v129
	v_fma_f32 v130, v130, v182, v183
	v_fma_f32 v131, v131, v182, v183
	v_fma_f32 v132, v132, v182, v183
	v_fma_f32 v133, v133, v182, v183
	v_mul_f32_e32 v130, v126, v130
	v_mul_f32_e32 v131, v127, v131
	v_mul_f32_e32 v132, v128, v132
	v_mul_f32_e32 v133, v129, v133
	v_exp_f32_e32 v130, v130
	v_exp_f32_e32 v131, v131
	v_exp_f32_e32 v132, v132
	v_exp_f32_e32 v133, v133
	v_add_f32_e32 v130, 1.0, v130
	v_add_f32_e32 v131, 1.0, v131
	v_add_f32_e32 v132, 1.0, v132
	v_add_f32_e32 v133, 1.0, v133
	v_rcp_f32_e32 v130, v130
	v_rcp_f32_e32 v131, v131
	v_rcp_f32_e32 v132, v132
	v_rcp_f32_e32 v133, v133
	s_nop 0
	v_mul_f32_e32 v126, v126, v130
	v_mul_f32_e32 v127, v127, v131
	v_mul_f32_e32 v128, v128, v132
	v_mul_f32_e32 v129, v129, v133
	v_cvt_pk_f16_f32 v126, v126, v127
	v_cvt_pk_f16_f32 v127, v128, v129
	global_store_dwordx2 v193, v[126:127], s[22:23] offset:0
	v_mul_f32_e32 v134, v122, v122
	v_mul_f32_e32 v135, v123, v123
	v_mul_f32_e32 v136, v124, v124
	v_mul_f32_e32 v137, v125, v125
	v_fma_f32 v134, v134, v182, v183
	v_fma_f32 v135, v135, v182, v183
	v_fma_f32 v136, v136, v182, v183
	v_fma_f32 v137, v137, v182, v183
	v_mul_f32_e32 v134, v122, v134
	v_mul_f32_e32 v135, v123, v135
	v_mul_f32_e32 v136, v124, v136
	v_mul_f32_e32 v137, v125, v137
	v_exp_f32_e32 v134, v134
	v_exp_f32_e32 v135, v135
	v_exp_f32_e32 v136, v136
	v_exp_f32_e32 v137, v137
	v_add_f32_e32 v134, 1.0, v134
	v_add_f32_e32 v135, 1.0, v135
	v_add_f32_e32 v136, 1.0, v136
	v_add_f32_e32 v137, 1.0, v137
	v_rcp_f32_e32 v134, v134
	v_rcp_f32_e32 v135, v135
	v_rcp_f32_e32 v136, v136
	v_rcp_f32_e32 v137, v137
	s_nop 0
	v_mul_f32_e32 v122, v122, v134
	v_mul_f32_e32 v123, v123, v135
	v_mul_f32_e32 v124, v124, v136
	v_mul_f32_e32 v125, v125, v137
	v_cvt_pk_f16_f32 v122, v122, v123
	v_cvt_pk_f16_f32 v123, v124, v125
	global_store_dwordx2 v193, v[122:123], s[22:23] offset:32
	v_mul_f32_e32 v130, v118, v118
	v_mul_f32_e32 v131, v119, v119
	v_mul_f32_e32 v132, v120, v120
	v_mul_f32_e32 v133, v121, v121
	v_fma_f32 v130, v130, v182, v183
	v_fma_f32 v131, v131, v182, v183
	v_fma_f32 v132, v132, v182, v183
	v_fma_f32 v133, v133, v182, v183
	v_mul_f32_e32 v130, v118, v130
	v_mul_f32_e32 v131, v119, v131
	v_mul_f32_e32 v132, v120, v132
	v_mul_f32_e32 v133, v121, v133
	v_exp_f32_e32 v130, v130
	v_exp_f32_e32 v131, v131
	v_exp_f32_e32 v132, v132
	v_exp_f32_e32 v133, v133
	v_add_f32_e32 v130, 1.0, v130
	v_add_f32_e32 v131, 1.0, v131
	v_add_f32_e32 v132, 1.0, v132
	v_add_f32_e32 v133, 1.0, v133
	v_rcp_f32_e32 v130, v130
	v_rcp_f32_e32 v131, v131
	v_rcp_f32_e32 v132, v132
	v_rcp_f32_e32 v133, v133
	s_nop 0
	v_mul_f32_e32 v118, v118, v130
	v_mul_f32_e32 v119, v119, v131
	v_mul_f32_e32 v120, v120, v132
	v_mul_f32_e32 v121, v121, v133
	v_cvt_pk_f16_f32 v118, v118, v119
	v_cvt_pk_f16_f32 v119, v120, v121
	global_store_dwordx2 v193, v[118:119], s[22:23] offset:64
	v_mul_f32_e32 v134, v114, v114
	v_mul_f32_e32 v135, v115, v115
	v_mul_f32_e32 v136, v116, v116
	v_mul_f32_e32 v137, v117, v117
	v_fma_f32 v134, v134, v182, v183
	v_fma_f32 v135, v135, v182, v183
	v_fma_f32 v136, v136, v182, v183
	v_fma_f32 v137, v137, v182, v183
	v_mul_f32_e32 v134, v114, v134
	v_mul_f32_e32 v135, v115, v135
	v_mul_f32_e32 v136, v116, v136
	v_mul_f32_e32 v137, v117, v137
	v_exp_f32_e32 v134, v134
	v_exp_f32_e32 v135, v135
	v_exp_f32_e32 v136, v136
	v_exp_f32_e32 v137, v137
	v_add_f32_e32 v134, 1.0, v134
	v_add_f32_e32 v135, 1.0, v135
	v_add_f32_e32 v136, 1.0, v136
	v_add_f32_e32 v137, 1.0, v137
	v_rcp_f32_e32 v134, v134
	v_rcp_f32_e32 v135, v135
	v_rcp_f32_e32 v136, v136
	v_rcp_f32_e32 v137, v137
	s_nop 0
	v_mul_f32_e32 v114, v114, v134
	v_mul_f32_e32 v115, v115, v135
	v_mul_f32_e32 v116, v116, v136
	v_mul_f32_e32 v117, v117, v137
	v_cvt_pk_f16_f32 v114, v114, v115
	v_cvt_pk_f16_f32 v115, v116, v117
	global_store_dwordx2 v193, v[114:115], s[22:23] offset:96
	v_add_u32_e32 v193, 0x2000, v193
	v_mul_f32_e32 v130, v110, v110
	v_mul_f32_e32 v131, v111, v111
	v_mul_f32_e32 v132, v112, v112
	v_mul_f32_e32 v133, v113, v113
	v_fma_f32 v130, v130, v182, v183
	v_fma_f32 v131, v131, v182, v183
	v_fma_f32 v132, v132, v182, v183
	v_fma_f32 v133, v133, v182, v183
	v_mul_f32_e32 v130, v110, v130
	v_mul_f32_e32 v131, v111, v131
	v_mul_f32_e32 v132, v112, v132
	v_mul_f32_e32 v133, v113, v133
	v_exp_f32_e32 v130, v130
	v_exp_f32_e32 v131, v131
	v_exp_f32_e32 v132, v132
	v_exp_f32_e32 v133, v133
	v_add_f32_e32 v130, 1.0, v130
	v_add_f32_e32 v131, 1.0, v131
	v_add_f32_e32 v132, 1.0, v132
	v_add_f32_e32 v133, 1.0, v133
	v_rcp_f32_e32 v130, v130
	v_rcp_f32_e32 v131, v131
	v_rcp_f32_e32 v132, v132
	v_rcp_f32_e32 v133, v133
	s_nop 0
	v_mul_f32_e32 v110, v110, v130
	v_mul_f32_e32 v111, v111, v131
	v_mul_f32_e32 v112, v112, v132
	v_mul_f32_e32 v113, v113, v133
	v_cvt_pk_f16_f32 v110, v110, v111
	v_cvt_pk_f16_f32 v111, v112, v113
	global_store_dwordx2 v193, v[110:111], s[22:23] offset:0
	v_mul_f32_e32 v134, v106, v106
	v_mul_f32_e32 v135, v107, v107
	v_mul_f32_e32 v136, v108, v108
	v_mul_f32_e32 v137, v109, v109
	v_fma_f32 v134, v134, v182, v183
	v_fma_f32 v135, v135, v182, v183
	v_fma_f32 v136, v136, v182, v183
	v_fma_f32 v137, v137, v182, v183
	v_mul_f32_e32 v134, v106, v134
	v_mul_f32_e32 v135, v107, v135
	v_mul_f32_e32 v136, v108, v136
	v_mul_f32_e32 v137, v109, v137
	v_exp_f32_e32 v134, v134
	v_exp_f32_e32 v135, v135
	v_exp_f32_e32 v136, v136
	v_exp_f32_e32 v137, v137
	v_add_f32_e32 v134, 1.0, v134
	v_add_f32_e32 v135, 1.0, v135
	v_add_f32_e32 v136, 1.0, v136
	v_add_f32_e32 v137, 1.0, v137
	v_rcp_f32_e32 v134, v134
	v_rcp_f32_e32 v135, v135
	v_rcp_f32_e32 v136, v136
	v_rcp_f32_e32 v137, v137
	s_nop 0
	v_mul_f32_e32 v106, v106, v134
	v_mul_f32_e32 v107, v107, v135
	v_mul_f32_e32 v108, v108, v136
	v_mul_f32_e32 v109, v109, v137
	v_cvt_pk_f16_f32 v106, v106, v107
	v_cvt_pk_f16_f32 v107, v108, v109
	global_store_dwordx2 v193, v[106:107], s[22:23] offset:32
	v_mul_f32_e32 v130, v102, v102
	v_mul_f32_e32 v131, v103, v103
	v_mul_f32_e32 v132, v104, v104
	v_mul_f32_e32 v133, v105, v105
	v_fma_f32 v130, v130, v182, v183
	v_fma_f32 v131, v131, v182, v183
	v_fma_f32 v132, v132, v182, v183
	v_fma_f32 v133, v133, v182, v183
	v_mul_f32_e32 v130, v102, v130
	v_mul_f32_e32 v131, v103, v131
	v_mul_f32_e32 v132, v104, v132
	v_mul_f32_e32 v133, v105, v133
	v_exp_f32_e32 v130, v130
	v_exp_f32_e32 v131, v131
	v_exp_f32_e32 v132, v132
	v_exp_f32_e32 v133, v133
	v_add_f32_e32 v130, 1.0, v130
	v_add_f32_e32 v131, 1.0, v131
	v_add_f32_e32 v132, 1.0, v132
	v_add_f32_e32 v133, 1.0, v133
	v_rcp_f32_e32 v130, v130
	v_rcp_f32_e32 v131, v131
	v_rcp_f32_e32 v132, v132
	v_rcp_f32_e32 v133, v133
	s_nop 0
	v_mul_f32_e32 v102, v102, v130
	v_mul_f32_e32 v103, v103, v131
	v_mul_f32_e32 v104, v104, v132
	v_mul_f32_e32 v105, v105, v133
	v_cvt_pk_f16_f32 v102, v102, v103
	v_cvt_pk_f16_f32 v103, v104, v105
	global_store_dwordx2 v193, v[102:103], s[22:23] offset:64
	v_mul_f32_e32 v134, v98, v98
	v_mul_f32_e32 v135, v99, v99
	v_mul_f32_e32 v136, v100, v100
	v_mul_f32_e32 v137, v101, v101
	v_fma_f32 v134, v134, v182, v183
	v_fma_f32 v135, v135, v182, v183
	v_fma_f32 v136, v136, v182, v183
	v_fma_f32 v137, v137, v182, v183
	v_mul_f32_e32 v134, v98, v134
	v_mul_f32_e32 v135, v99, v135
	v_mul_f32_e32 v136, v100, v136
	v_mul_f32_e32 v137, v101, v137
	v_exp_f32_e32 v134, v134
	v_exp_f32_e32 v135, v135
	v_exp_f32_e32 v136, v136
	v_exp_f32_e32 v137, v137
	v_add_f32_e32 v134, 1.0, v134
	v_add_f32_e32 v135, 1.0, v135
	v_add_f32_e32 v136, 1.0, v136
	v_add_f32_e32 v137, 1.0, v137
	v_rcp_f32_e32 v134, v134
	v_rcp_f32_e32 v135, v135
	v_rcp_f32_e32 v136, v136
	v_rcp_f32_e32 v137, v137
	s_nop 0
	v_mul_f32_e32 v98, v98, v134
	v_mul_f32_e32 v99, v99, v135
	v_mul_f32_e32 v100, v100, v136
	v_mul_f32_e32 v101, v101, v137
	v_cvt_pk_f16_f32 v98, v98, v99
	v_cvt_pk_f16_f32 v99, v100, v101
	global_store_dwordx2 v193, v[98:99], s[22:23] offset:96
	v_add_u32_e32 v193, 0x2000, v193
	v_mul_f32_e32 v130, v94, v94
	v_mul_f32_e32 v131, v95, v95
	v_mul_f32_e32 v132, v96, v96
	v_mul_f32_e32 v133, v97, v97
	v_fma_f32 v130, v130, v182, v183
	v_fma_f32 v131, v131, v182, v183
	v_fma_f32 v132, v132, v182, v183
	v_fma_f32 v133, v133, v182, v183
	v_mul_f32_e32 v130, v94, v130
	v_mul_f32_e32 v131, v95, v131
	v_mul_f32_e32 v132, v96, v132
	v_mul_f32_e32 v133, v97, v133
	v_exp_f32_e32 v130, v130
	v_exp_f32_e32 v131, v131
	v_exp_f32_e32 v132, v132
	v_exp_f32_e32 v133, v133
	v_add_f32_e32 v130, 1.0, v130
	v_add_f32_e32 v131, 1.0, v131
	v_add_f32_e32 v132, 1.0, v132
	v_add_f32_e32 v133, 1.0, v133
	v_rcp_f32_e32 v130, v130
	v_rcp_f32_e32 v131, v131
	v_rcp_f32_e32 v132, v132
	v_rcp_f32_e32 v133, v133
	s_nop 0
	v_mul_f32_e32 v94, v94, v130
	v_mul_f32_e32 v95, v95, v131
	v_mul_f32_e32 v96, v96, v132
	v_mul_f32_e32 v97, v97, v133
	v_cvt_pk_f16_f32 v94, v94, v95
	v_cvt_pk_f16_f32 v95, v96, v97
	global_store_dwordx2 v193, v[94:95], s[22:23] offset:0
	v_mul_f32_e32 v134, v90, v90
	v_mul_f32_e32 v135, v91, v91
	v_mul_f32_e32 v136, v92, v92
	v_mul_f32_e32 v137, v93, v93
	v_fma_f32 v134, v134, v182, v183
	v_fma_f32 v135, v135, v182, v183
	v_fma_f32 v136, v136, v182, v183
	v_fma_f32 v137, v137, v182, v183
	v_mul_f32_e32 v134, v90, v134
	v_mul_f32_e32 v135, v91, v135
	v_mul_f32_e32 v136, v92, v136
	v_mul_f32_e32 v137, v93, v137
	v_exp_f32_e32 v134, v134
	v_exp_f32_e32 v135, v135
	v_exp_f32_e32 v136, v136
	v_exp_f32_e32 v137, v137
	v_add_f32_e32 v134, 1.0, v134
	v_add_f32_e32 v135, 1.0, v135
	v_add_f32_e32 v136, 1.0, v136
	v_add_f32_e32 v137, 1.0, v137
	v_rcp_f32_e32 v134, v134
	v_rcp_f32_e32 v135, v135
	v_rcp_f32_e32 v136, v136
	v_rcp_f32_e32 v137, v137
	s_nop 0
	v_mul_f32_e32 v90, v90, v134
	v_mul_f32_e32 v91, v91, v135
	v_mul_f32_e32 v92, v92, v136
	v_mul_f32_e32 v93, v93, v137
	v_cvt_pk_f16_f32 v90, v90, v91
	v_cvt_pk_f16_f32 v91, v92, v93
	global_store_dwordx2 v193, v[90:91], s[22:23] offset:32
	v_mul_f32_e32 v130, v86, v86
	v_mul_f32_e32 v131, v87, v87
	v_mul_f32_e32 v132, v88, v88
	v_mul_f32_e32 v133, v89, v89
	v_fma_f32 v130, v130, v182, v183
	v_fma_f32 v131, v131, v182, v183
	v_fma_f32 v132, v132, v182, v183
	v_fma_f32 v133, v133, v182, v183
	v_mul_f32_e32 v130, v86, v130
	v_mul_f32_e32 v131, v87, v131
	v_mul_f32_e32 v132, v88, v132
	v_mul_f32_e32 v133, v89, v133
	v_exp_f32_e32 v130, v130
	v_exp_f32_e32 v131, v131
	v_exp_f32_e32 v132, v132
	v_exp_f32_e32 v133, v133
	v_add_f32_e32 v130, 1.0, v130
	v_add_f32_e32 v131, 1.0, v131
	v_add_f32_e32 v132, 1.0, v132
	v_add_f32_e32 v133, 1.0, v133
	v_rcp_f32_e32 v130, v130
	v_rcp_f32_e32 v131, v131
	v_rcp_f32_e32 v132, v132
	v_rcp_f32_e32 v133, v133
	s_nop 0
	v_mul_f32_e32 v86, v86, v130
	v_mul_f32_e32 v87, v87, v131
	v_mul_f32_e32 v88, v88, v132
	v_mul_f32_e32 v89, v89, v133
	v_cvt_pk_f16_f32 v86, v86, v87
	v_cvt_pk_f16_f32 v87, v88, v89
	global_store_dwordx2 v193, v[86:87], s[22:23] offset:64
	v_mul_f32_e32 v134, v82, v82
	v_mul_f32_e32 v135, v83, v83
	v_mul_f32_e32 v136, v84, v84
	v_mul_f32_e32 v137, v85, v85
	v_fma_f32 v134, v134, v182, v183
	v_fma_f32 v135, v135, v182, v183
	v_fma_f32 v136, v136, v182, v183
	v_fma_f32 v137, v137, v182, v183
	v_mul_f32_e32 v134, v82, v134
	v_mul_f32_e32 v135, v83, v135
	v_mul_f32_e32 v136, v84, v136
	v_mul_f32_e32 v137, v85, v137
	v_exp_f32_e32 v134, v134
	v_exp_f32_e32 v135, v135
	v_exp_f32_e32 v136, v136
	v_exp_f32_e32 v137, v137
	v_add_f32_e32 v134, 1.0, v134
	v_add_f32_e32 v135, 1.0, v135
	v_add_f32_e32 v136, 1.0, v136
	v_add_f32_e32 v137, 1.0, v137
	v_rcp_f32_e32 v134, v134
	v_rcp_f32_e32 v135, v135
	v_rcp_f32_e32 v136, v136
	v_rcp_f32_e32 v137, v137
	s_nop 0
	v_mul_f32_e32 v82, v82, v134
	v_mul_f32_e32 v83, v83, v135
	v_mul_f32_e32 v84, v84, v136
	v_mul_f32_e32 v85, v85, v137
	v_cvt_pk_f16_f32 v82, v82, v83
	v_cvt_pk_f16_f32 v83, v84, v85
	global_store_dwordx2 v193, v[82:83], s[22:23] offset:96
	v_add_u32_e32 v193, 0x2000, v193
	v_mul_f32_e32 v130, v78, v78
	v_mul_f32_e32 v131, v79, v79
	v_mul_f32_e32 v132, v80, v80
	v_mul_f32_e32 v133, v81, v81
	v_fma_f32 v130, v130, v182, v183
	v_fma_f32 v131, v131, v182, v183
	v_fma_f32 v132, v132, v182, v183
	v_fma_f32 v133, v133, v182, v183
	v_mul_f32_e32 v130, v78, v130
	v_mul_f32_e32 v131, v79, v131
	v_mul_f32_e32 v132, v80, v132
	v_mul_f32_e32 v133, v81, v133
	v_exp_f32_e32 v130, v130
	v_exp_f32_e32 v131, v131
	v_exp_f32_e32 v132, v132
	v_exp_f32_e32 v133, v133
	v_add_f32_e32 v130, 1.0, v130
	v_add_f32_e32 v131, 1.0, v131
	v_add_f32_e32 v132, 1.0, v132
	v_add_f32_e32 v133, 1.0, v133
	v_rcp_f32_e32 v130, v130
	v_rcp_f32_e32 v131, v131
	v_rcp_f32_e32 v132, v132
	v_rcp_f32_e32 v133, v133
	s_nop 0
	v_mul_f32_e32 v78, v78, v130
	v_mul_f32_e32 v79, v79, v131
	v_mul_f32_e32 v80, v80, v132
	v_mul_f32_e32 v81, v81, v133
	v_cvt_pk_f16_f32 v78, v78, v79
	v_cvt_pk_f16_f32 v79, v80, v81
	global_store_dwordx2 v193, v[78:79], s[22:23] offset:0
	v_mul_f32_e32 v134, v74, v74
	v_mul_f32_e32 v135, v75, v75
	v_mul_f32_e32 v136, v76, v76
	v_mul_f32_e32 v137, v77, v77
	v_fma_f32 v134, v134, v182, v183
	v_fma_f32 v135, v135, v182, v183
	v_fma_f32 v136, v136, v182, v183
	v_fma_f32 v137, v137, v182, v183
	v_mul_f32_e32 v134, v74, v134
	v_mul_f32_e32 v135, v75, v135
	v_mul_f32_e32 v136, v76, v136
	v_mul_f32_e32 v137, v77, v137
	v_exp_f32_e32 v134, v134
	v_exp_f32_e32 v135, v135
	v_exp_f32_e32 v136, v136
	v_exp_f32_e32 v137, v137
	v_add_f32_e32 v134, 1.0, v134
	v_add_f32_e32 v135, 1.0, v135
	v_add_f32_e32 v136, 1.0, v136
	v_add_f32_e32 v137, 1.0, v137
	v_rcp_f32_e32 v134, v134
	v_rcp_f32_e32 v135, v135
	v_rcp_f32_e32 v136, v136
	v_rcp_f32_e32 v137, v137
	s_nop 0
	v_mul_f32_e32 v74, v74, v134
	v_mul_f32_e32 v75, v75, v135
	v_mul_f32_e32 v76, v76, v136
	v_mul_f32_e32 v77, v77, v137
	v_cvt_pk_f16_f32 v74, v74, v75
	v_cvt_pk_f16_f32 v75, v76, v77
	global_store_dwordx2 v193, v[74:75], s[22:23] offset:32
	v_mul_f32_e32 v130, v70, v70
	v_mul_f32_e32 v131, v71, v71
	v_mul_f32_e32 v132, v72, v72
	v_mul_f32_e32 v133, v73, v73
	v_fma_f32 v130, v130, v182, v183
	v_fma_f32 v131, v131, v182, v183
	v_fma_f32 v132, v132, v182, v183
	v_fma_f32 v133, v133, v182, v183
	v_mul_f32_e32 v130, v70, v130
	v_mul_f32_e32 v131, v71, v131
	v_mul_f32_e32 v132, v72, v132
	v_mul_f32_e32 v133, v73, v133
	v_exp_f32_e32 v130, v130
	v_exp_f32_e32 v131, v131
	v_exp_f32_e32 v132, v132
	v_exp_f32_e32 v133, v133
	v_add_f32_e32 v130, 1.0, v130
	v_add_f32_e32 v131, 1.0, v131
	v_add_f32_e32 v132, 1.0, v132
	v_add_f32_e32 v133, 1.0, v133
	v_rcp_f32_e32 v130, v130
	v_rcp_f32_e32 v131, v131
	v_rcp_f32_e32 v132, v132
	v_rcp_f32_e32 v133, v133
	s_nop 0
	v_mul_f32_e32 v70, v70, v130
	v_mul_f32_e32 v71, v71, v131
	v_mul_f32_e32 v72, v72, v132
	v_mul_f32_e32 v73, v73, v133
	v_cvt_pk_f16_f32 v70, v70, v71
	v_cvt_pk_f16_f32 v71, v72, v73
	global_store_dwordx2 v193, v[70:71], s[22:23] offset:64
	v_mul_f32_e32 v134, v66, v66
	v_mul_f32_e32 v135, v67, v67
	v_mul_f32_e32 v136, v68, v68
	v_mul_f32_e32 v137, v69, v69
	v_fma_f32 v134, v134, v182, v183
	v_fma_f32 v135, v135, v182, v183
	v_fma_f32 v136, v136, v182, v183
	v_fma_f32 v137, v137, v182, v183
	v_mul_f32_e32 v134, v66, v134
	v_mul_f32_e32 v135, v67, v135
	v_mul_f32_e32 v136, v68, v136
	v_mul_f32_e32 v137, v69, v137
	v_exp_f32_e32 v134, v134
	v_exp_f32_e32 v135, v135
	v_exp_f32_e32 v136, v136
	v_exp_f32_e32 v137, v137
	v_add_f32_e32 v134, 1.0, v134
	v_add_f32_e32 v135, 1.0, v135
	v_add_f32_e32 v136, 1.0, v136
	v_add_f32_e32 v137, 1.0, v137
	v_rcp_f32_e32 v134, v134
	v_rcp_f32_e32 v135, v135
	v_rcp_f32_e32 v136, v136
	v_rcp_f32_e32 v137, v137
	s_nop 0
	v_mul_f32_e32 v66, v66, v134
	v_mul_f32_e32 v67, v67, v135
	v_mul_f32_e32 v68, v68, v136
	v_mul_f32_e32 v69, v69, v137
	v_cvt_pk_f16_f32 v66, v66, v67
	v_cvt_pk_f16_f32 v67, v68, v69
	global_store_dwordx2 v193, v[66:67], s[22:23] offset:96
	v_add_u32_e32 v193, 0x2000, v193
	v_mul_f32_e32 v130, v62, v62
	v_mul_f32_e32 v131, v63, v63
	v_mul_f32_e32 v132, v64, v64
	v_mul_f32_e32 v133, v65, v65
	v_fma_f32 v130, v130, v182, v183
	v_fma_f32 v131, v131, v182, v183
	v_fma_f32 v132, v132, v182, v183
	v_fma_f32 v133, v133, v182, v183
	v_mul_f32_e32 v130, v62, v130
	v_mul_f32_e32 v131, v63, v131
	v_mul_f32_e32 v132, v64, v132
	v_mul_f32_e32 v133, v65, v133
	v_exp_f32_e32 v130, v130
	v_exp_f32_e32 v131, v131
	v_exp_f32_e32 v132, v132
	v_exp_f32_e32 v133, v133
	v_add_f32_e32 v130, 1.0, v130
	v_add_f32_e32 v131, 1.0, v131
	v_add_f32_e32 v132, 1.0, v132
	v_add_f32_e32 v133, 1.0, v133
	v_rcp_f32_e32 v130, v130
	v_rcp_f32_e32 v131, v131
	v_rcp_f32_e32 v132, v132
	v_rcp_f32_e32 v133, v133
	s_nop 0
	v_mul_f32_e32 v62, v62, v130
	v_mul_f32_e32 v63, v63, v131
	v_mul_f32_e32 v64, v64, v132
	v_mul_f32_e32 v65, v65, v133
	v_cvt_pk_f16_f32 v62, v62, v63
	v_cvt_pk_f16_f32 v63, v64, v65
	global_store_dwordx2 v193, v[62:63], s[22:23] offset:0
	v_mul_f32_e32 v134, v58, v58
	v_mul_f32_e32 v135, v59, v59
	v_mul_f32_e32 v136, v60, v60
	v_mul_f32_e32 v137, v61, v61
	v_fma_f32 v134, v134, v182, v183
	v_fma_f32 v135, v135, v182, v183
	v_fma_f32 v136, v136, v182, v183
	v_fma_f32 v137, v137, v182, v183
	v_mul_f32_e32 v134, v58, v134
	v_mul_f32_e32 v135, v59, v135
	v_mul_f32_e32 v136, v60, v136
	v_mul_f32_e32 v137, v61, v137
	v_exp_f32_e32 v134, v134
	v_exp_f32_e32 v135, v135
	v_exp_f32_e32 v136, v136
	v_exp_f32_e32 v137, v137
	v_add_f32_e32 v134, 1.0, v134
	v_add_f32_e32 v135, 1.0, v135
	v_add_f32_e32 v136, 1.0, v136
	v_add_f32_e32 v137, 1.0, v137
	v_rcp_f32_e32 v134, v134
	v_rcp_f32_e32 v135, v135
	v_rcp_f32_e32 v136, v136
	v_rcp_f32_e32 v137, v137
	s_nop 0
	v_mul_f32_e32 v58, v58, v134
	v_mul_f32_e32 v59, v59, v135
	v_mul_f32_e32 v60, v60, v136
	v_mul_f32_e32 v61, v61, v137
	v_cvt_pk_f16_f32 v58, v58, v59
	v_cvt_pk_f16_f32 v59, v60, v61
	global_store_dwordx2 v193, v[58:59], s[22:23] offset:32
	v_mul_f32_e32 v130, v54, v54
	v_mul_f32_e32 v131, v55, v55
	v_mul_f32_e32 v132, v56, v56
	v_mul_f32_e32 v133, v57, v57
	v_fma_f32 v130, v130, v182, v183
	v_fma_f32 v131, v131, v182, v183
	v_fma_f32 v132, v132, v182, v183
	v_fma_f32 v133, v133, v182, v183
	v_mul_f32_e32 v130, v54, v130
	v_mul_f32_e32 v131, v55, v131
	v_mul_f32_e32 v132, v56, v132
	v_mul_f32_e32 v133, v57, v133
	v_exp_f32_e32 v130, v130
	v_exp_f32_e32 v131, v131
	v_exp_f32_e32 v132, v132
	v_exp_f32_e32 v133, v133
	v_add_f32_e32 v130, 1.0, v130
	v_add_f32_e32 v131, 1.0, v131
	v_add_f32_e32 v132, 1.0, v132
	v_add_f32_e32 v133, 1.0, v133
	v_rcp_f32_e32 v130, v130
	v_rcp_f32_e32 v131, v131
	v_rcp_f32_e32 v132, v132
	v_rcp_f32_e32 v133, v133
	s_nop 0
	v_mul_f32_e32 v54, v54, v130
	v_mul_f32_e32 v55, v55, v131
	v_mul_f32_e32 v56, v56, v132
	v_mul_f32_e32 v57, v57, v133
	v_cvt_pk_f16_f32 v54, v54, v55
	v_cvt_pk_f16_f32 v55, v56, v57
	global_store_dwordx2 v193, v[54:55], s[22:23] offset:64
	v_mul_f32_e32 v134, v50, v50
	v_mul_f32_e32 v135, v51, v51
	v_mul_f32_e32 v136, v52, v52
	v_mul_f32_e32 v137, v53, v53
	v_fma_f32 v134, v134, v182, v183
	v_fma_f32 v135, v135, v182, v183
	v_fma_f32 v136, v136, v182, v183
	v_fma_f32 v137, v137, v182, v183
	v_mul_f32_e32 v134, v50, v134
	v_mul_f32_e32 v135, v51, v135
	v_mul_f32_e32 v136, v52, v136
	v_mul_f32_e32 v137, v53, v137
	v_exp_f32_e32 v134, v134
	v_exp_f32_e32 v135, v135
	v_exp_f32_e32 v136, v136
	v_exp_f32_e32 v137, v137
	v_add_f32_e32 v134, 1.0, v134
	v_add_f32_e32 v135, 1.0, v135
	v_add_f32_e32 v136, 1.0, v136
	v_add_f32_e32 v137, 1.0, v137
	v_rcp_f32_e32 v134, v134
	v_rcp_f32_e32 v135, v135
	v_rcp_f32_e32 v136, v136
	v_rcp_f32_e32 v137, v137
	s_nop 0
	v_mul_f32_e32 v50, v50, v134
	v_mul_f32_e32 v51, v51, v135
	v_mul_f32_e32 v52, v52, v136
	v_mul_f32_e32 v53, v53, v137
	v_cvt_pk_f16_f32 v50, v50, v51
	v_cvt_pk_f16_f32 v51, v52, v53
	global_store_dwordx2 v193, v[50:51], s[22:23] offset:96
	v_add_u32_e32 v193, 0x2000, v193
	v_mul_f32_e32 v130, v46, v46
	v_mul_f32_e32 v131, v47, v47
	v_mul_f32_e32 v132, v48, v48
	v_mul_f32_e32 v133, v49, v49
	v_fma_f32 v130, v130, v182, v183
	v_fma_f32 v131, v131, v182, v183
	v_fma_f32 v132, v132, v182, v183
	v_fma_f32 v133, v133, v182, v183
	v_mul_f32_e32 v130, v46, v130
	v_mul_f32_e32 v131, v47, v131
	v_mul_f32_e32 v132, v48, v132
	v_mul_f32_e32 v133, v49, v133
	v_exp_f32_e32 v130, v130
	v_exp_f32_e32 v131, v131
	v_exp_f32_e32 v132, v132
	v_exp_f32_e32 v133, v133
	v_add_f32_e32 v130, 1.0, v130
	v_add_f32_e32 v131, 1.0, v131
	v_add_f32_e32 v132, 1.0, v132
	v_add_f32_e32 v133, 1.0, v133
	v_rcp_f32_e32 v130, v130
	v_rcp_f32_e32 v131, v131
	v_rcp_f32_e32 v132, v132
	v_rcp_f32_e32 v133, v133
	s_nop 0
	v_mul_f32_e32 v46, v46, v130
	v_mul_f32_e32 v47, v47, v131
	v_mul_f32_e32 v48, v48, v132
	v_mul_f32_e32 v49, v49, v133
	v_cvt_pk_f16_f32 v46, v46, v47
	v_cvt_pk_f16_f32 v47, v48, v49
	global_store_dwordx2 v193, v[46:47], s[22:23] offset:0
	v_mul_f32_e32 v134, v42, v42
	v_mul_f32_e32 v135, v43, v43
	v_mul_f32_e32 v136, v44, v44
	v_mul_f32_e32 v137, v45, v45
	v_fma_f32 v134, v134, v182, v183
	v_fma_f32 v135, v135, v182, v183
	v_fma_f32 v136, v136, v182, v183
	v_fma_f32 v137, v137, v182, v183
	v_mul_f32_e32 v134, v42, v134
	v_mul_f32_e32 v135, v43, v135
	v_mul_f32_e32 v136, v44, v136
	v_mul_f32_e32 v137, v45, v137
	v_exp_f32_e32 v134, v134
	v_exp_f32_e32 v135, v135
	v_exp_f32_e32 v136, v136
	v_exp_f32_e32 v137, v137
	v_add_f32_e32 v134, 1.0, v134
	v_add_f32_e32 v135, 1.0, v135
	v_add_f32_e32 v136, 1.0, v136
	v_add_f32_e32 v137, 1.0, v137
	v_rcp_f32_e32 v134, v134
	v_rcp_f32_e32 v135, v135
	v_rcp_f32_e32 v136, v136
	v_rcp_f32_e32 v137, v137
	s_nop 0
	v_mul_f32_e32 v42, v42, v134
	v_mul_f32_e32 v43, v43, v135
	v_mul_f32_e32 v44, v44, v136
	v_mul_f32_e32 v45, v45, v137
	v_cvt_pk_f16_f32 v42, v42, v43
	v_cvt_pk_f16_f32 v43, v44, v45
	global_store_dwordx2 v193, v[42:43], s[22:23] offset:32
	v_mul_f32_e32 v130, v38, v38
	v_mul_f32_e32 v131, v39, v39
	v_mul_f32_e32 v132, v40, v40
	v_mul_f32_e32 v133, v41, v41
	v_fma_f32 v130, v130, v182, v183
	v_fma_f32 v131, v131, v182, v183
	v_fma_f32 v132, v132, v182, v183
	v_fma_f32 v133, v133, v182, v183
	v_mul_f32_e32 v130, v38, v130
	v_mul_f32_e32 v131, v39, v131
	v_mul_f32_e32 v132, v40, v132
	v_mul_f32_e32 v133, v41, v133
	v_exp_f32_e32 v130, v130
	v_exp_f32_e32 v131, v131
	v_exp_f32_e32 v132, v132
	v_exp_f32_e32 v133, v133
	v_add_f32_e32 v130, 1.0, v130
	v_add_f32_e32 v131, 1.0, v131
	v_add_f32_e32 v132, 1.0, v132
	v_add_f32_e32 v133, 1.0, v133
	v_rcp_f32_e32 v130, v130
	v_rcp_f32_e32 v131, v131
	v_rcp_f32_e32 v132, v132
	v_rcp_f32_e32 v133, v133
	s_nop 0
	v_mul_f32_e32 v38, v38, v130
	v_mul_f32_e32 v39, v39, v131
	v_mul_f32_e32 v40, v40, v132
	v_mul_f32_e32 v41, v41, v133
	v_cvt_pk_f16_f32 v38, v38, v39
	v_cvt_pk_f16_f32 v39, v40, v41
	global_store_dwordx2 v193, v[38:39], s[22:23] offset:64
	v_mul_f32_e32 v134, v34, v34
	v_mul_f32_e32 v135, v35, v35
	v_mul_f32_e32 v136, v36, v36
	v_mul_f32_e32 v137, v37, v37
	v_fma_f32 v134, v134, v182, v183
	v_fma_f32 v135, v135, v182, v183
	v_fma_f32 v136, v136, v182, v183
	v_fma_f32 v137, v137, v182, v183
	v_mul_f32_e32 v134, v34, v134
	v_mul_f32_e32 v135, v35, v135
	v_mul_f32_e32 v136, v36, v136
	v_mul_f32_e32 v137, v37, v137
	v_exp_f32_e32 v134, v134
	v_exp_f32_e32 v135, v135
	v_exp_f32_e32 v136, v136
	v_exp_f32_e32 v137, v137
	v_add_f32_e32 v134, 1.0, v134
	v_add_f32_e32 v135, 1.0, v135
	v_add_f32_e32 v136, 1.0, v136
	v_add_f32_e32 v137, 1.0, v137
	v_rcp_f32_e32 v134, v134
	v_rcp_f32_e32 v135, v135
	v_rcp_f32_e32 v136, v136
	v_rcp_f32_e32 v137, v137
	s_nop 0
	v_mul_f32_e32 v34, v34, v134
	v_mul_f32_e32 v35, v35, v135
	v_mul_f32_e32 v36, v36, v136
	v_mul_f32_e32 v37, v37, v137
	v_cvt_pk_f16_f32 v34, v34, v35
	v_cvt_pk_f16_f32 v35, v36, v37
	global_store_dwordx2 v193, v[34:35], s[22:23] offset:96
	v_add_u32_e32 v193, 0x2000, v193
	v_mul_f32_e32 v130, v30, v30
	v_mul_f32_e32 v131, v31, v31
	v_mul_f32_e32 v132, v32, v32
	v_mul_f32_e32 v133, v33, v33
	v_fma_f32 v130, v130, v182, v183
	v_fma_f32 v131, v131, v182, v183
	v_fma_f32 v132, v132, v182, v183
	v_fma_f32 v133, v133, v182, v183
	v_mul_f32_e32 v130, v30, v130
	v_mul_f32_e32 v131, v31, v131
	v_mul_f32_e32 v132, v32, v132
	v_mul_f32_e32 v133, v33, v133
	v_exp_f32_e32 v130, v130
	v_exp_f32_e32 v131, v131
	v_exp_f32_e32 v132, v132
	v_exp_f32_e32 v133, v133
	v_add_f32_e32 v130, 1.0, v130
	v_add_f32_e32 v131, 1.0, v131
	v_add_f32_e32 v132, 1.0, v132
	v_add_f32_e32 v133, 1.0, v133
	v_rcp_f32_e32 v130, v130
	v_rcp_f32_e32 v131, v131
	v_rcp_f32_e32 v132, v132
	v_rcp_f32_e32 v133, v133
	s_nop 0
	v_mul_f32_e32 v30, v30, v130
	v_mul_f32_e32 v31, v31, v131
	v_mul_f32_e32 v32, v32, v132
	v_mul_f32_e32 v33, v33, v133
	v_cvt_pk_f16_f32 v30, v30, v31
	v_cvt_pk_f16_f32 v31, v32, v33
	global_store_dwordx2 v193, v[30:31], s[22:23] offset:0
	v_mul_f32_e32 v134, v26, v26
	v_mul_f32_e32 v135, v27, v27
	v_mul_f32_e32 v136, v28, v28
	v_mul_f32_e32 v137, v29, v29
	v_fma_f32 v134, v134, v182, v183
	v_fma_f32 v135, v135, v182, v183
	v_fma_f32 v136, v136, v182, v183
	v_fma_f32 v137, v137, v182, v183
	v_mul_f32_e32 v134, v26, v134
	v_mul_f32_e32 v135, v27, v135
	v_mul_f32_e32 v136, v28, v136
	v_mul_f32_e32 v137, v29, v137
	v_exp_f32_e32 v134, v134
	v_exp_f32_e32 v135, v135
	v_exp_f32_e32 v136, v136
	v_exp_f32_e32 v137, v137
	v_add_f32_e32 v134, 1.0, v134
	v_add_f32_e32 v135, 1.0, v135
	v_add_f32_e32 v136, 1.0, v136
	v_add_f32_e32 v137, 1.0, v137
	v_rcp_f32_e32 v134, v134
	v_rcp_f32_e32 v135, v135
	v_rcp_f32_e32 v136, v136
	v_rcp_f32_e32 v137, v137
	s_nop 0
	v_mul_f32_e32 v26, v26, v134
	v_mul_f32_e32 v27, v27, v135
	v_mul_f32_e32 v28, v28, v136
	v_mul_f32_e32 v29, v29, v137
	v_cvt_pk_f16_f32 v26, v26, v27
	v_cvt_pk_f16_f32 v27, v28, v29
	global_store_dwordx2 v193, v[26:27], s[22:23] offset:32
	v_mul_f32_e32 v130, v22, v22
	v_mul_f32_e32 v131, v23, v23
	v_mul_f32_e32 v132, v24, v24
	v_mul_f32_e32 v133, v25, v25
	v_fma_f32 v130, v130, v182, v183
	v_fma_f32 v131, v131, v182, v183
	v_fma_f32 v132, v132, v182, v183
	v_fma_f32 v133, v133, v182, v183
	v_mul_f32_e32 v130, v22, v130
	v_mul_f32_e32 v131, v23, v131
	v_mul_f32_e32 v132, v24, v132
	v_mul_f32_e32 v133, v25, v133
	v_exp_f32_e32 v130, v130
	v_exp_f32_e32 v131, v131
	v_exp_f32_e32 v132, v132
	v_exp_f32_e32 v133, v133
	v_add_f32_e32 v130, 1.0, v130
	v_add_f32_e32 v131, 1.0, v131
	v_add_f32_e32 v132, 1.0, v132
	v_add_f32_e32 v133, 1.0, v133
	v_rcp_f32_e32 v130, v130
	v_rcp_f32_e32 v131, v131
	v_rcp_f32_e32 v132, v132
	v_rcp_f32_e32 v133, v133
	s_nop 0
	v_mul_f32_e32 v22, v22, v130
	v_mul_f32_e32 v23, v23, v131
	v_mul_f32_e32 v24, v24, v132
	v_mul_f32_e32 v25, v25, v133
	v_cvt_pk_f16_f32 v22, v22, v23
	v_cvt_pk_f16_f32 v23, v24, v25
	global_store_dwordx2 v193, v[22:23], s[22:23] offset:64
	v_mul_f32_e32 v134, v18, v18
	v_mul_f32_e32 v135, v19, v19
	v_mul_f32_e32 v136, v20, v20
	v_mul_f32_e32 v137, v21, v21
	v_fma_f32 v134, v134, v182, v183
	v_fma_f32 v135, v135, v182, v183
	v_fma_f32 v136, v136, v182, v183
	v_fma_f32 v137, v137, v182, v183
	v_mul_f32_e32 v134, v18, v134
	v_mul_f32_e32 v135, v19, v135
	v_mul_f32_e32 v136, v20, v136
	v_mul_f32_e32 v137, v21, v137
	v_exp_f32_e32 v134, v134
	v_exp_f32_e32 v135, v135
	v_exp_f32_e32 v136, v136
	v_exp_f32_e32 v137, v137
	v_add_f32_e32 v134, 1.0, v134
	v_add_f32_e32 v135, 1.0, v135
	v_add_f32_e32 v136, 1.0, v136
	v_add_f32_e32 v137, 1.0, v137
	v_rcp_f32_e32 v134, v134
	v_rcp_f32_e32 v135, v135
	v_rcp_f32_e32 v136, v136
	v_rcp_f32_e32 v137, v137
	s_nop 0
	v_mul_f32_e32 v18, v18, v134
	v_mul_f32_e32 v19, v19, v135
	v_mul_f32_e32 v20, v20, v136
	v_mul_f32_e32 v21, v21, v137
	v_cvt_pk_f16_f32 v18, v18, v19
	v_cvt_pk_f16_f32 v19, v20, v21
	global_store_dwordx2 v193, v[18:19], s[22:23] offset:96
	v_add_u32_e32 v193, 0x2000, v193
	v_mul_f32_e32 v130, v14, v14
	v_mul_f32_e32 v131, v15, v15
	v_mul_f32_e32 v132, v16, v16
	v_mul_f32_e32 v133, v17, v17
	v_fma_f32 v130, v130, v182, v183
	v_fma_f32 v131, v131, v182, v183
	v_fma_f32 v132, v132, v182, v183
	v_fma_f32 v133, v133, v182, v183
	v_mul_f32_e32 v130, v14, v130
	v_mul_f32_e32 v131, v15, v131
	v_mul_f32_e32 v132, v16, v132
	v_mul_f32_e32 v133, v17, v133
	v_exp_f32_e32 v130, v130
	v_exp_f32_e32 v131, v131
	v_exp_f32_e32 v132, v132
	v_exp_f32_e32 v133, v133
	v_add_f32_e32 v130, 1.0, v130
	v_add_f32_e32 v131, 1.0, v131
	v_add_f32_e32 v132, 1.0, v132
	v_add_f32_e32 v133, 1.0, v133
	v_rcp_f32_e32 v130, v130
	v_rcp_f32_e32 v131, v131
	v_rcp_f32_e32 v132, v132
	v_rcp_f32_e32 v133, v133
	s_nop 0
	v_mul_f32_e32 v14, v14, v130
	v_mul_f32_e32 v15, v15, v131
	v_mul_f32_e32 v16, v16, v132
	v_mul_f32_e32 v17, v17, v133
	v_cvt_pk_f16_f32 v14, v14, v15
	v_cvt_pk_f16_f32 v15, v16, v17
	global_store_dwordx2 v193, v[14:15], s[22:23] offset:0
	v_mul_f32_e32 v134, v10, v10
	v_mul_f32_e32 v135, v11, v11
	v_mul_f32_e32 v136, v12, v12
	v_mul_f32_e32 v137, v13, v13
	v_fma_f32 v134, v134, v182, v183
	v_fma_f32 v135, v135, v182, v183
	v_fma_f32 v136, v136, v182, v183
	v_fma_f32 v137, v137, v182, v183
	v_mul_f32_e32 v134, v10, v134
	v_mul_f32_e32 v135, v11, v135
	v_mul_f32_e32 v136, v12, v136
	v_mul_f32_e32 v137, v13, v137
	v_exp_f32_e32 v134, v134
	v_exp_f32_e32 v135, v135
	v_exp_f32_e32 v136, v136
	v_exp_f32_e32 v137, v137
	v_add_f32_e32 v134, 1.0, v134
	v_add_f32_e32 v135, 1.0, v135
	v_add_f32_e32 v136, 1.0, v136
	v_add_f32_e32 v137, 1.0, v137
	v_rcp_f32_e32 v134, v134
	v_rcp_f32_e32 v135, v135
	v_rcp_f32_e32 v136, v136
	v_rcp_f32_e32 v137, v137
	s_nop 0
	v_mul_f32_e32 v10, v10, v134
	v_mul_f32_e32 v11, v11, v135
	v_mul_f32_e32 v12, v12, v136
	v_mul_f32_e32 v13, v13, v137
	v_cvt_pk_f16_f32 v10, v10, v11
	v_cvt_pk_f16_f32 v11, v12, v13
	global_store_dwordx2 v193, v[10:11], s[22:23] offset:32
	v_mul_f32_e32 v130, v6, v6
	v_mul_f32_e32 v131, v7, v7
	v_mul_f32_e32 v132, v8, v8
	v_mul_f32_e32 v133, v9, v9
	v_fma_f32 v130, v130, v182, v183
	v_fma_f32 v131, v131, v182, v183
	v_fma_f32 v132, v132, v182, v183
	v_fma_f32 v133, v133, v182, v183
	v_mul_f32_e32 v130, v6, v130
	v_mul_f32_e32 v131, v7, v131
	v_mul_f32_e32 v132, v8, v132
	v_mul_f32_e32 v133, v9, v133
	v_exp_f32_e32 v130, v130
	v_exp_f32_e32 v131, v131
	v_exp_f32_e32 v132, v132
	v_exp_f32_e32 v133, v133
	v_add_f32_e32 v130, 1.0, v130
	v_add_f32_e32 v131, 1.0, v131
	v_add_f32_e32 v132, 1.0, v132
	v_add_f32_e32 v133, 1.0, v133
	v_rcp_f32_e32 v130, v130
	v_rcp_f32_e32 v131, v131
	v_rcp_f32_e32 v132, v132
	v_rcp_f32_e32 v133, v133
	s_nop 0
	v_mul_f32_e32 v6, v6, v130
	v_mul_f32_e32 v7, v7, v131
	v_mul_f32_e32 v8, v8, v132
	v_mul_f32_e32 v9, v9, v133
	v_cvt_pk_f16_f32 v6, v6, v7
	v_cvt_pk_f16_f32 v7, v8, v9
	global_store_dwordx2 v193, v[6:7], s[22:23] offset:64
	v_mul_f32_e32 v134, v2, v2
	v_mul_f32_e32 v135, v3, v3
	v_mul_f32_e32 v136, v4, v4
	v_mul_f32_e32 v137, v5, v5
	v_fma_f32 v134, v134, v182, v183
	v_fma_f32 v135, v135, v182, v183
	v_fma_f32 v136, v136, v182, v183
	v_fma_f32 v137, v137, v182, v183
	v_mul_f32_e32 v134, v2, v134
	v_mul_f32_e32 v135, v3, v135
	v_mul_f32_e32 v136, v4, v136
	v_mul_f32_e32 v137, v5, v137
	v_exp_f32_e32 v134, v134
	v_exp_f32_e32 v135, v135
	v_exp_f32_e32 v136, v136
	v_exp_f32_e32 v137, v137
	v_add_f32_e32 v134, 1.0, v134
	v_add_f32_e32 v135, 1.0, v135
	v_add_f32_e32 v136, 1.0, v136
	v_add_f32_e32 v137, 1.0, v137
	v_rcp_f32_e32 v134, v134
	v_rcp_f32_e32 v135, v135
	v_rcp_f32_e32 v136, v136
	v_rcp_f32_e32 v137, v137
	s_nop 0
	v_mul_f32_e32 v2, v2, v134
	v_mul_f32_e32 v3, v3, v135
	v_mul_f32_e32 v4, v4, v136
	v_mul_f32_e32 v5, v5, v137
	v_cvt_pk_f16_f32 v2, v2, v3
	v_cvt_pk_f16_f32 v3, v4, v5
	global_store_dwordx2 v193, v[2:3], s[22:23] offset:96
	s_waitcnt vmcnt(32)
	s_branch .Lp1_join
